# GEMM epilogues (FFN-out residual, output-projection residual, both merge GEMMs, MLA up-projections): row loads issued in one batch ahead of the stores via cloned address chains, vmcnt waits re-derived
# speedup vs baseline: 1.0043x; 1.0035x over previous
.LBB0_782:
	s_lshl_b32 s26, s62, 8
	s_add_i32 s62, s26, s51
	s_lshl_b32 s26, s63, 8
	v_mov_b32_e32 v138, v0
	s_ashr_i32 s27, s26, 31
	s_lshl_b64 s[28:29], s[26:27], 2
	v_lshrrev_b32_e32 v18, 1, v138
	v_and_or_b32 v179, v18, 24, s52
	s_add_u32 s28, s48, s28
	s_addc_u32 s29, s49, s29
	v_lshlrev_b32_e32 v42, 2, v179
	global_load_dwordx4 v[18:21], v42, s[28:29] offset:16
	global_load_dwordx4 v[26:29], v42, s[28:29]
	global_load_dwordx4 v[170:173], v42, s[28:29] offset:528
	global_load_dwordx4 v[174:177], v42, s[28:29] offset:512
	v_and_or_b32 v188, v138, 15, s62
	v_ashrrev_i32_e32 v189, 31, v188
	v_lshl_add_u64 v[190:191], v[188:189], 2, s[14:15]
	global_load_dword v186, v[190:191], off
	global_load_dword v156, v[190:191], off offset:704
	v_or_b32_e32 v184, 16, v188
	v_ashrrev_i32_e32 v185, 31, v184
	v_lshl_add_u64 v[158:159], v[184:185], 2, s[14:15]
	global_load_dword v182, v[158:159], off
	v_or_b32_e32 v180, 32, v188
	v_ashrrev_i32_e32 v181, 31, v180
	v_lshl_add_u64 v[158:159], v[180:181], 2, s[14:15]
	global_load_dword v178, v[158:159], off
	s_lshl_b64 s[26:27], s[26:27], 1
	v_lshlrev_b32_e32 v138, 1, v179
	v_add_u32_e32 v169, 0xa0, v188
	s_and_b64 vcc, exec, s[0:1]
	s_waitcnt vmcnt(0)
	v_pk_mul_f32 v[18:19], v[18:19], s[22:23] op_sel_hi:[1,0]
	v_pk_mul_f32 v[154:155], v[28:29], s[22:23] op_sel_hi:[1,0]
	v_pk_mul_f32 v[152:153], v[176:177], s[22:23] op_sel_hi:[1,0]
	v_or_b32_e32 v176, 48, v188
	v_ashrrev_i32_e32 v177, 31, v176
	v_pk_mul_f32 v[28:29], v[172:173], s[22:23] op_sel_hi:[1,0]
	global_load_dword v172, v[190:191], off offset:512
	v_lshl_add_u64 v[158:159], v[176:177], 2, s[14:15]
	v_pk_mul_f32 v[42:43], v[174:175], s[22:23] op_sel_hi:[1,0]
	global_load_dword v174, v[158:159], off
	v_pk_mul_f32 v[44:45], v[26:27], s[22:23] op_sel_hi:[1,0]
	v_pk_mul_f32 v[26:27], v[20:21], s[22:23] op_sel_hi:[1,0]
	v_pk_mul_f32 v[20:21], v[170:171], s[22:23] op_sel_hi:[1,0]
	global_load_dword v170, v[190:191], off offset:576
	global_load_dword v158, v[190:191], off offset:640
	v_pk_mul_f32 v[160:161], v[154:155], v[160:161]
	v_pk_mul_f32 v[162:163], v[44:45], v[162:163]
	v_pk_mul_f32 v[160:161], v[160:161], v[186:187] op_sel_hi:[1,0]
	v_pk_mul_f32 v[162:163], v[162:163], v[186:187] op_sel_hi:[1,0]
	v_pk_mul_f32 v[166:167], v[26:27], v[166:167]
	v_pk_mul_f32 v[164:165], v[18:19], v[164:165]
	v_pk_mul_f32 v[166:167], v[166:167], v[186:187] op_sel_hi:[1,0]
	v_pk_mul_f32 v[164:165], v[164:165], v[186:187] op_sel_hi:[1,0]
	v_cvt_pk_bf16_f32 v162, v162, v163
	v_cvt_pk_bf16_f32 v163, v160, v161
	v_mov_b64_e32 v[160:161], s[12:13]
	v_cvt_pk_bf16_f32 v164, v164, v165
	v_cvt_pk_bf16_f32 v165, v166, v167
	v_mad_i64_i32 v[166:167], s[28:29], v188, s59, v[160:161]
	v_lshl_add_u64 v[166:167], v[166:167], 0, s[26:27]
	v_lshl_add_u64 v[166:167], v[166:167], 0, v[138:139]
	v_pk_mul_f32 v[150:151], v[152:153], v[150:151]
	v_pk_mul_f32 v[148:149], v[42:43], v[148:149]
	v_pk_mul_f32 v[128:129], v[28:29], v[128:129]
	v_pk_mul_f32 v[126:127], v[20:21], v[126:127]
	global_store_dwordx4 v[166:167], v[162:165], off
	v_pk_mul_f32 v[150:151], v[150:151], v[186:187] op_sel_hi:[1,0]
	v_pk_mul_f32 v[148:149], v[148:149], v[186:187] op_sel_hi:[1,0]
	v_pk_mul_f32 v[162:163], v[128:129], v[186:187] op_sel_hi:[1,0]
	v_pk_mul_f32 v[128:129], v[126:127], v[186:187] op_sel_hi:[1,0]
	v_pk_mul_f32 v[122:123], v[44:45], v[122:123]
	v_cvt_pk_bf16_f32 v126, v148, v149
	v_cvt_pk_bf16_f32 v127, v150, v151
	v_cvt_pk_bf16_f32 v128, v128, v129
	v_cvt_pk_bf16_f32 v129, v162, v163
	v_pk_mul_f32 v[122:123], v[122:123], v[182:183] op_sel_hi:[1,0]
	v_pk_mul_f32 v[120:121], v[26:27], v[120:121]
	v_pk_mul_f32 v[118:119], v[18:19], v[118:119]
	global_store_dwordx4 v[166:167], v[126:129], off offset:256
	v_pk_mul_f32 v[124:125], v[154:155], v[124:125]
	v_pk_mul_f32 v[116:117], v[152:153], v[116:117]
	v_pk_mul_f32 v[126:127], v[120:121], v[182:183] op_sel_hi:[1,0]
	v_pk_mul_f32 v[120:121], v[118:119], v[182:183] op_sel_hi:[1,0]
	v_cvt_pk_bf16_f32 v118, v122, v123
	v_mad_i64_i32 v[122:123], s[28:29], v184, s59, v[160:161]
	v_pk_mul_f32 v[124:125], v[124:125], v[182:183] op_sel_hi:[1,0]
	v_lshl_add_u64 v[122:123], v[122:123], 0, s[26:27]
	v_cvt_pk_bf16_f32 v119, v124, v125
	v_cvt_pk_bf16_f32 v120, v120, v121
	v_cvt_pk_bf16_f32 v121, v126, v127
	v_lshl_add_u64 v[122:123], v[122:123], 0, v[138:139]
	v_pk_mul_f32 v[112:113], v[42:43], v[112:113]
	v_pk_mul_f32 v[114:115], v[28:29], v[114:115]
	v_pk_mul_f32 v[110:111], v[20:21], v[110:111]
	global_store_dwordx4 v[122:123], v[118:121], off
	v_pk_mul_f32 v[116:117], v[116:117], v[182:183] op_sel_hi:[1,0]
	v_pk_mul_f32 v[112:113], v[112:113], v[182:183] op_sel_hi:[1,0]
	v_pk_mul_f32 v[114:115], v[114:115], v[182:183] op_sel_hi:[1,0]
	v_pk_mul_f32 v[118:119], v[110:111], v[182:183] op_sel_hi:[1,0]
	v_pk_mul_f32 v[96:97], v[44:45], v[96:97]
	v_pk_mul_f32 v[98:99], v[26:27], v[98:99]
	v_cvt_pk_bf16_f32 v110, v112, v113
	v_cvt_pk_bf16_f32 v111, v116, v117
	v_cvt_pk_bf16_f32 v112, v118, v119
	v_cvt_pk_bf16_f32 v113, v114, v115
	v_pk_mul_f32 v[96:97], v[96:97], v[178:179] op_sel_hi:[1,0]
	v_pk_mul_f32 v[94:95], v[18:19], v[94:95]
	v_pk_mul_f32 v[98:99], v[98:99], v[178:179] op_sel_hi:[1,0]
	global_store_dwordx4 v[122:123], v[110:113], off offset:256
	v_pk_mul_f32 v[102:103], v[154:155], v[102:103]
	v_pk_mul_f32 v[100:101], v[20:21], v[100:101]
	v_pk_mul_f32 v[110:111], v[94:95], v[178:179] op_sel_hi:[1,0]
	v_cvt_pk_bf16_f32 v94, v96, v97
	v_cvt_pk_bf16_f32 v97, v98, v99
	v_mad_i64_i32 v[98:99], s[28:29], v180, s59, v[160:161]
	v_pk_mul_f32 v[102:103], v[102:103], v[178:179] op_sel_hi:[1,0]
	v_lshl_add_u64 v[98:99], v[98:99], 0, s[26:27]
	v_cvt_pk_bf16_f32 v95, v102, v103
	v_cvt_pk_bf16_f32 v96, v110, v111
	v_lshl_add_u64 v[98:99], v[98:99], 0, v[138:139]
	global_store_dwordx4 v[98:99], v[94:97], off
	v_pk_mul_f32 v[76:77], v[44:45], v[76:77]
	v_pk_mul_f32 v[78:79], v[26:27], v[78:79]
	v_pk_mul_f32 v[94:95], v[152:153], v[108:109]
	v_pk_mul_f32 v[96:97], v[42:43], v[104:105]
	v_pk_mul_f32 v[102:103], v[94:95], v[178:179] op_sel_hi:[1,0]
	v_pk_mul_f32 v[94:95], v[96:97], v[178:179] op_sel_hi:[1,0]
	v_pk_mul_f32 v[96:97], v[28:29], v[106:107]
	v_cvt_pk_bf16_f32 v94, v94, v95
	v_pk_mul_f32 v[104:105], v[96:97], v[178:179] op_sel_hi:[1,0]
	v_pk_mul_f32 v[96:97], v[100:101], v[178:179] op_sel_hi:[1,0]
	v_cvt_pk_bf16_f32 v95, v102, v103
	v_cvt_pk_bf16_f32 v96, v96, v97
	v_cvt_pk_bf16_f32 v97, v104, v105
	s_waitcnt vmcnt(0)
	v_pk_mul_f32 v[76:77], v[76:77], v[174:175] op_sel_hi:[1,0]
	v_pk_mul_f32 v[74:75], v[18:19], v[74:75]
	v_pk_mul_f32 v[78:79], v[78:79], v[174:175] op_sel_hi:[1,0]
	global_store_dwordx4 v[98:99], v[94:97], off offset:256
	v_pk_mul_f32 v[80:81], v[154:155], v[80:81]
	v_add_u32_e32 v173, 0x80, v188
	v_pk_mul_f32 v[94:95], v[74:75], v[174:175] op_sel_hi:[1,0]
	v_cvt_pk_bf16_f32 v74, v76, v77
	v_cvt_pk_bf16_f32 v77, v78, v79
	v_mad_i64_i32 v[78:79], s[28:29], v176, s59, v[160:161]
	v_pk_mul_f32 v[80:81], v[80:81], v[174:175] op_sel_hi:[1,0]
	v_lshl_add_u64 v[78:79], v[78:79], 0, s[26:27]
	v_cvt_pk_bf16_f32 v75, v80, v81
	v_cvt_pk_bf16_f32 v76, v94, v95
	v_lshl_add_u64 v[78:79], v[78:79], 0, v[138:139]
	global_store_dwordx4 v[78:79], v[74:77], off
	v_pk_mul_f32 v[70:71], v[20:21], v[70:71]
	v_pk_mul_f32 v[66:67], v[44:45], v[66:67]
	v_pk_mul_f32 v[74:75], v[152:153], v[88:89]
	v_pk_mul_f32 v[76:77], v[42:43], v[82:83]
	v_pk_mul_f32 v[80:81], v[74:75], v[174:175] op_sel_hi:[1,0]
	v_pk_mul_f32 v[74:75], v[76:77], v[174:175] op_sel_hi:[1,0]
	v_pk_mul_f32 v[76:77], v[28:29], v[86:87]
	v_pk_mul_f32 v[70:71], v[70:71], v[174:175] op_sel_hi:[1,0]
	v_pk_mul_f32 v[66:67], v[66:67], v[172:173] op_sel_hi:[1,0]
	v_pk_mul_f32 v[64:65], v[26:27], v[64:65]
	v_pk_mul_f32 v[62:63], v[18:19], v[62:63]
	v_pk_mul_f32 v[82:83], v[76:77], v[174:175] op_sel_hi:[1,0]
	v_cvt_pk_bf16_f32 v76, v70, v71
	v_pk_mul_f32 v[68:69], v[154:155], v[68:69]
	v_pk_mul_f32 v[70:71], v[64:65], v[172:173] op_sel_hi:[1,0]
	v_pk_mul_f32 v[64:65], v[62:63], v[172:173] op_sel_hi:[1,0]
	v_cvt_pk_bf16_f32 v62, v66, v67
	v_mad_i64_i32 v[66:67], s[28:29], v173, s59, v[160:161]
	v_pk_mul_f32 v[68:69], v[68:69], v[172:173] op_sel_hi:[1,0]
	v_lshl_add_u64 v[66:67], v[66:67], 0, s[26:27]
	v_cvt_pk_bf16_f32 v63, v68, v69
	v_cvt_pk_bf16_f32 v64, v64, v65
	v_cvt_pk_bf16_f32 v65, v70, v71
	v_lshl_add_u64 v[66:67], v[66:67], 0, v[138:139]
	global_store_dwordx4 v[66:67], v[62:65], off
	v_pk_mul_f32 v[70:71], v[20:21], v[72:73]
	v_add_u32_e32 v171, 0x90, v188
	v_pk_mul_f32 v[62:63], v[152:153], v[92:93]
	v_pk_mul_f32 v[64:65], v[42:43], v[84:85]
	v_pk_mul_f32 v[68:69], v[62:63], v[172:173] op_sel_hi:[1,0]
	v_pk_mul_f32 v[62:63], v[64:65], v[172:173] op_sel_hi:[1,0]
	v_pk_mul_f32 v[64:65], v[28:29], v[90:91]
	v_pk_mul_f32 v[48:49], v[44:45], v[48:49]
	v_pk_mul_f32 v[72:73], v[64:65], v[172:173] op_sel_hi:[1,0]
	v_pk_mul_f32 v[64:65], v[70:71], v[172:173] op_sel_hi:[1,0]
	v_pk_mul_f32 v[50:51], v[26:27], v[50:51]
	v_cvt_pk_bf16_f32 v62, v62, v63
	v_cvt_pk_bf16_f32 v63, v68, v69
	v_cvt_pk_bf16_f32 v64, v64, v65
	v_cvt_pk_bf16_f32 v65, v72, v73
	v_pk_mul_f32 v[48:49], v[48:49], v[170:171] op_sel_hi:[1,0]
	v_pk_mul_f32 v[46:47], v[18:19], v[46:47]
	v_pk_mul_f32 v[50:51], v[50:51], v[170:171] op_sel_hi:[1,0]
	global_store_dwordx4 v[66:67], v[62:65], off offset:256
	v_pk_mul_f32 v[54:55], v[154:155], v[54:55]
	v_pk_mul_f32 v[52:53], v[20:21], v[52:53]
	v_pk_mul_f32 v[62:63], v[46:47], v[170:171] op_sel_hi:[1,0]
	v_cvt_pk_bf16_f32 v46, v48, v49
	v_cvt_pk_bf16_f32 v49, v50, v51
	v_mad_i64_i32 v[50:51], s[28:29], v171, s59, v[160:161]
	v_pk_mul_f32 v[54:55], v[54:55], v[170:171] op_sel_hi:[1,0]
	v_lshl_add_u64 v[50:51], v[50:51], 0, s[26:27]
	v_cvt_pk_bf16_f32 v47, v54, v55
	v_cvt_pk_bf16_f32 v48, v62, v63
	v_lshl_add_u64 v[50:51], v[50:51], 0, v[138:139]
	global_store_dwordx4 v[50:51], v[46:49], off
	v_add_u32_e32 v159, 0xb0, v188
	v_pk_mul_f32 v[24:25], v[44:45], v[24:25]
	v_pk_mul_f32 v[46:47], v[152:153], v[60:61]
	v_pk_mul_f32 v[48:49], v[42:43], v[56:57]
	v_pk_mul_f32 v[54:55], v[46:47], v[170:171] op_sel_hi:[1,0]
	v_pk_mul_f32 v[46:47], v[48:49], v[170:171] op_sel_hi:[1,0]
	v_pk_mul_f32 v[48:49], v[28:29], v[58:59]
	v_pk_mul_f32 v[30:31], v[26:27], v[30:31]
	v_pk_mul_f32 v[56:57], v[48:49], v[170:171] op_sel_hi:[1,0]
	v_pk_mul_f32 v[48:49], v[52:53], v[170:171] op_sel_hi:[1,0]
	v_cvt_pk_bf16_f32 v46, v46, v47
	v_cvt_pk_bf16_f32 v47, v54, v55
	v_cvt_pk_bf16_f32 v48, v48, v49
	v_cvt_pk_bf16_f32 v49, v56, v57
	v_pk_mul_f32 v[24:25], v[24:25], v[158:159] op_sel_hi:[1,0]
	v_pk_mul_f32 v[22:23], v[18:19], v[22:23]
	v_pk_mul_f32 v[30:31], v[30:31], v[158:159] op_sel_hi:[1,0]
	global_store_dwordx4 v[50:51], v[46:49], off offset:256
	v_pk_mul_f32 v[32:33], v[154:155], v[32:33]
	v_pk_mul_f32 v[12:13], v[44:45], v[12:13]
	v_pk_mul_f32 v[46:47], v[22:23], v[158:159] op_sel_hi:[1,0]
	v_cvt_pk_bf16_f32 v22, v24, v25
	v_cvt_pk_bf16_f32 v25, v30, v31
	v_mad_i64_i32 v[30:31], s[28:29], v169, s59, v[160:161]
	v_pk_mul_f32 v[14:15], v[26:27], v[14:15]
	v_pk_mul_f32 v[32:33], v[32:33], v[158:159] op_sel_hi:[1,0]
	v_lshl_add_u64 v[30:31], v[30:31], 0, s[26:27]
	v_pk_mul_f32 v[12:13], v[12:13], v[156:157] op_sel_hi:[1,0]
	v_pk_mul_f32 v[10:11], v[18:19], v[10:11]
	v_pk_mul_f32 v[14:15], v[14:15], v[156:157] op_sel_hi:[1,0]
	v_cvt_pk_bf16_f32 v23, v32, v33
	v_cvt_pk_bf16_f32 v24, v46, v47
	v_lshl_add_u64 v[30:31], v[30:31], 0, v[138:139]
	v_pk_mul_f32 v[16:17], v[154:155], v[16:17]
	v_pk_mul_f32 v[18:19], v[10:11], v[156:157] op_sel_hi:[1,0]
	v_cvt_pk_bf16_f32 v10, v12, v13
	v_cvt_pk_bf16_f32 v13, v14, v15
	v_mad_i64_i32 v[14:15], s[28:29], v159, s59, v[160:161]
	global_store_dwordx4 v[30:31], v[22:25], off
	v_pk_mul_f32 v[16:17], v[16:17], v[156:157] op_sel_hi:[1,0]
	v_lshl_add_u64 v[14:15], v[14:15], 0, s[26:27]
	v_pk_mul_f32 v[22:23], v[152:153], v[40:41]
	v_pk_mul_f32 v[24:25], v[42:43], v[36:37]
	v_pk_mul_f32 v[32:33], v[22:23], v[158:159] op_sel_hi:[1,0]
	v_pk_mul_f32 v[22:23], v[24:25], v[158:159] op_sel_hi:[1,0]
	v_pk_mul_f32 v[24:25], v[28:29], v[38:39]
	v_pk_mul_f32 v[34:35], v[20:21], v[34:35]
	v_cvt_pk_bf16_f32 v11, v16, v17
	v_cvt_pk_bf16_f32 v12, v18, v19
	v_lshl_add_u64 v[14:15], v[14:15], 0, v[138:139]
	v_pk_mul_f32 v[8:9], v[152:153], v[8:9]
	v_pk_mul_f32 v[6:7], v[42:43], v[6:7]
	v_pk_mul_f32 v[4:5], v[28:29], v[4:5]
	v_pk_mul_f32 v[2:3], v[20:21], v[2:3]
	v_pk_mul_f32 v[36:37], v[24:25], v[158:159] op_sel_hi:[1,0]
	v_pk_mul_f32 v[24:25], v[34:35], v[158:159] op_sel_hi:[1,0]
	global_store_dwordx4 v[14:15], v[10:13], off
	v_pk_mul_f32 v[8:9], v[8:9], v[156:157] op_sel_hi:[1,0]
	v_pk_mul_f32 v[6:7], v[6:7], v[156:157] op_sel_hi:[1,0]
	v_pk_mul_f32 v[10:11], v[4:5], v[156:157] op_sel_hi:[1,0]
	v_pk_mul_f32 v[4:5], v[2:3], v[156:157] op_sel_hi:[1,0]
	v_cvt_pk_bf16_f32 v74, v74, v75
	v_cvt_pk_bf16_f32 v75, v80, v81
	v_cvt_pk_bf16_f32 v77, v82, v83
	v_cvt_pk_bf16_f32 v22, v22, v23
	v_cvt_pk_bf16_f32 v23, v32, v33
	v_cvt_pk_bf16_f32 v24, v24, v25
	v_cvt_pk_bf16_f32 v25, v36, v37
	v_cvt_pk_bf16_f32 v2, v6, v7
	v_cvt_pk_bf16_f32 v3, v8, v9
	v_cvt_pk_bf16_f32 v4, v4, v5
	v_cvt_pk_bf16_f32 v5, v10, v11
	s_mov_b64 s[26:27], -1
	global_store_dwordx4 v[78:79], v[74:77], off offset:256
	global_store_dwordx4 v[30:31], v[22:25], off offset:256
	global_store_dwordx4 v[14:15], v[2:5], off offset:256
	s_cbranch_vccnz .LBB0_769
	s_andn2_b64 vcc, exec, s[10:11]
	s_cbranch_vccnz .LBB0_768
	s_barrier
	s_branch .LBB0_768

.LBB0_804:
	s_lshl_b32 s26, s59, 8
	s_add_i32 s59, s26, s49
	s_lshl_b32 s26, s60, 8
	v_mov_b32_e32 v126, v0
	s_ashr_i32 s27, s26, 31
	s_lshl_b64 s[28:29], s[26:27], 2
	v_lshrrev_b32_e32 v2, 1, v126
	v_and_or_b32 v127, v2, 24, s50
	s_add_u32 s28, s46, s28
	s_addc_u32 s29, s47, s29
	v_lshlrev_b32_e32 v42, 2, v127
	global_load_dwordx4 v[2:5], v42, s[28:29] offset:16
	global_load_dwordx4 v[26:29], v42, s[28:29]
	v_and_or_b32 v190, v126, 15, s59
	v_ashrrev_i32_e32 v191, 31, v190
	v_or_b32_e32 v188, 16, v190
	v_ashrrev_i32_e32 v189, 31, v188
	v_or_b32_e32 v184, 32, v190
	v_ashrrev_i32_e32 v185, 31, v184
	v_or_b32_e32 v180, 48, v190
	v_ashrrev_i32_e32 v181, 31, v180
	s_lshl_b64 s[26:27], s[26:27], 1
	v_lshlrev_b32_e32 v138, 1, v127
	global_load_dwordx4 v[194:197], v42, s[28:29] offset:528
	s_waitcnt vmcnt(0)
	v_pk_mul_f32 v[122:123], v[28:29], s[22:23] op_sel_hi:[1,0]
	v_pk_mul_f32 v[118:119], v[26:27], s[22:23] op_sel_hi:[1,0]
	v_pk_mul_f32 v[28:29], v[4:5], s[22:23] op_sel_hi:[1,0]
	v_pk_mul_f32 v[26:27], v[2:3], s[22:23] op_sel_hi:[1,0]
	s_nop 0
	global_load_dwordx4 v[42:45], v42, s[28:29] offset:512
	v_pk_mul_f32 v[94:95], v[26:27], v[94:95]
	v_pk_mul_f32 v[74:75], v[26:27], v[74:75]
	v_pk_mul_f32 v[62:63], v[26:27], v[62:63]
	v_pk_mul_f32 v[46:47], v[26:27], v[46:47]
	v_pk_mul_f32 v[22:23], v[26:27], v[22:23]
	v_pk_mul_f32 v[10:11], v[26:27], v[10:11]
	s_waitcnt vmcnt(0)
	v_pk_mul_f32 v[120:121], v[42:43], s[22:23] op_sel_hi:[1,0]
	v_pk_mul_f32 v[42:43], v[194:195], s[22:23] op_sel_hi:[1,0]
	v_lshl_add_u64 v[194:195], v[190:191], 2, s[14:15]
	global_load_dword v192, v[194:195], off
	v_pk_mul_f32 v[124:125], v[44:45], s[22:23] op_sel_hi:[1,0]
	v_pk_mul_f32 v[44:45], v[196:197], s[22:23] op_sel_hi:[1,0]
	v_lshl_add_u64 v[196:197], v[188:189], 2, s[14:15]
	global_load_dword v186, v[196:197], off
	v_lshl_add_u64 v[196:197], v[184:185], 2, s[14:15]
	global_load_dword v182, v[196:197], off
	v_lshl_add_u64 v[196:197], v[180:181], 2, s[14:15]
	global_load_dword v178, v[196:197], off
	global_load_dword v170, v[194:195], off offset:512
	global_load_dword v156, v[194:195], off offset:576
	global_load_dword v128, v[194:195], off offset:640
	global_load_dword v126, v[194:195], off offset:704
	v_pk_mul_f32 v[2:3], v[122:123], v[166:167]
	v_pk_mul_f32 v[4:5], v[118:119], v[172:173]
	v_pk_mul_f32 v[172:173], v[26:27], v[174:175]
	v_pk_mul_f32 v[110:111], v[42:43], v[110:111]
	v_pk_mul_f32 v[6:7], v[42:43], v[6:7]
	s_waitcnt vmcnt(7)
	v_pk_mul_f32 v[166:167], v[2:3], v[192:193] op_sel_hi:[1,0]
	v_pk_mul_f32 v[2:3], v[4:5], v[192:193] op_sel_hi:[1,0]
	v_pk_mul_f32 v[4:5], v[28:29], v[176:177]
	v_cvt_pk_bf16_f32 v2, v2, v3
	v_cvt_pk_bf16_f32 v3, v166, v167
	v_lshlrev_b64 v[166:167], 13, v[190:191]
	v_lshl_add_u64 v[166:167], s[12:13], 0, v[166:167]
	v_pk_mul_f32 v[174:175], v[4:5], v[192:193] op_sel_hi:[1,0]
	v_pk_mul_f32 v[4:5], v[172:173], v[192:193] op_sel_hi:[1,0]
	v_lshl_add_u64 v[166:167], v[166:167], 0, s[26:27]
	v_cvt_pk_bf16_f32 v4, v4, v5
	v_cvt_pk_bf16_f32 v5, v174, v175
	v_lshl_add_u64 v[166:167], v[166:167], 0, v[138:139]
	global_store_dwordx4 v[166:167], v[2:5], off
	s_nop 1
	v_pk_mul_f32 v[2:3], v[124:125], v[160:161]
	v_pk_mul_f32 v[4:5], v[120:121], v[158:159]
	v_pk_mul_f32 v[158:159], v[2:3], v[192:193] op_sel_hi:[1,0]
	v_pk_mul_f32 v[2:3], v[4:5], v[192:193] op_sel_hi:[1,0]
	v_pk_mul_f32 v[4:5], v[44:45], v[164:165]
	v_pk_mul_f32 v[160:161], v[42:43], v[162:163]
	v_pk_mul_f32 v[162:163], v[4:5], v[192:193] op_sel_hi:[1,0]
	v_pk_mul_f32 v[4:5], v[160:161], v[192:193] op_sel_hi:[1,0]
	v_cvt_pk_bf16_f32 v2, v2, v3
	v_cvt_pk_bf16_f32 v3, v158, v159
	v_cvt_pk_bf16_f32 v4, v4, v5
	v_cvt_pk_bf16_f32 v5, v162, v163
	global_store_dwordx4 v[166:167], v[2:5], off offset:256
	s_nop 1
	v_pk_mul_f32 v[2:3], v[122:123], v[150:151]
	v_pk_mul_f32 v[4:5], v[118:119], v[148:149]
	s_waitcnt vmcnt(0)
	v_pk_mul_f32 v[148:149], v[2:3], v[186:187] op_sel_hi:[1,0]
	v_pk_mul_f32 v[2:3], v[4:5], v[186:187] op_sel_hi:[1,0]
	v_pk_mul_f32 v[4:5], v[28:29], v[154:155]
	v_cvt_pk_bf16_f32 v2, v2, v3
	v_cvt_pk_bf16_f32 v3, v148, v149
	v_lshlrev_b64 v[148:149], 13, v[188:189]
	v_pk_mul_f32 v[150:151], v[26:27], v[152:153]
	v_lshl_add_u64 v[148:149], s[12:13], 0, v[148:149]
	v_pk_mul_f32 v[152:153], v[4:5], v[186:187] op_sel_hi:[1,0]
	v_pk_mul_f32 v[4:5], v[150:151], v[186:187] op_sel_hi:[1,0]
	v_lshl_add_u64 v[148:149], v[148:149], 0, s[26:27]
	v_cvt_pk_bf16_f32 v4, v4, v5
	v_cvt_pk_bf16_f32 v5, v152, v153
	v_lshl_add_u64 v[148:149], v[148:149], 0, v[138:139]
	global_store_dwordx4 v[148:149], v[2:5], off
	s_nop 1
	v_pk_mul_f32 v[2:3], v[124:125], v[116:117]
	v_pk_mul_f32 v[4:5], v[120:121], v[112:113]
	v_pk_mul_f32 v[112:113], v[2:3], v[186:187] op_sel_hi:[1,0]
	v_pk_mul_f32 v[2:3], v[4:5], v[186:187] op_sel_hi:[1,0]
	v_pk_mul_f32 v[4:5], v[44:45], v[114:115]
	v_cvt_pk_bf16_f32 v2, v2, v3
	v_pk_mul_f32 v[114:115], v[4:5], v[186:187] op_sel_hi:[1,0]
	v_pk_mul_f32 v[4:5], v[110:111], v[186:187] op_sel_hi:[1,0]
	v_cvt_pk_bf16_f32 v3, v112, v113
	v_cvt_pk_bf16_f32 v4, v4, v5
	v_cvt_pk_bf16_f32 v5, v114, v115
	global_store_dwordx4 v[148:149], v[2:5], off offset:256
	s_nop 1
	v_pk_mul_f32 v[2:3], v[122:123], v[102:103]
	v_pk_mul_f32 v[4:5], v[118:119], v[96:97]
	v_pk_mul_f32 v[96:97], v[2:3], v[182:183] op_sel_hi:[1,0]
	v_pk_mul_f32 v[2:3], v[4:5], v[182:183] op_sel_hi:[1,0]
	v_pk_mul_f32 v[4:5], v[28:29], v[98:99]
	v_cvt_pk_bf16_f32 v2, v2, v3
	v_pk_mul_f32 v[98:99], v[4:5], v[182:183] op_sel_hi:[1,0]
	v_pk_mul_f32 v[4:5], v[94:95], v[182:183] op_sel_hi:[1,0]
	v_lshlrev_b64 v[94:95], 13, v[184:185]
	v_lshl_add_u64 v[94:95], s[12:13], 0, v[94:95]
	v_lshl_add_u64 v[94:95], v[94:95], 0, s[26:27]
	v_cvt_pk_bf16_f32 v3, v96, v97
	v_cvt_pk_bf16_f32 v4, v4, v5
	v_cvt_pk_bf16_f32 v5, v98, v99
	v_lshl_add_u64 v[94:95], v[94:95], 0, v[138:139]
	global_store_dwordx4 v[94:95], v[2:5], off
	v_pk_mul_f32 v[98:99], v[42:43], v[100:101]
	s_nop 0
	v_pk_mul_f32 v[2:3], v[124:125], v[108:109]
	v_pk_mul_f32 v[4:5], v[120:121], v[104:105]
	v_pk_mul_f32 v[96:97], v[2:3], v[182:183] op_sel_hi:[1,0]
	v_pk_mul_f32 v[2:3], v[4:5], v[182:183] op_sel_hi:[1,0]
	v_pk_mul_f32 v[4:5], v[44:45], v[106:107]
	v_cvt_pk_bf16_f32 v2, v2, v3
	v_pk_mul_f32 v[100:101], v[4:5], v[182:183] op_sel_hi:[1,0]
	v_pk_mul_f32 v[4:5], v[98:99], v[182:183] op_sel_hi:[1,0]
	v_cvt_pk_bf16_f32 v3, v96, v97
	v_cvt_pk_bf16_f32 v4, v4, v5
	v_cvt_pk_bf16_f32 v5, v100, v101
	global_store_dwordx4 v[94:95], v[2:5], off offset:256
	s_nop 1
	v_pk_mul_f32 v[2:3], v[122:123], v[80:81]
	v_pk_mul_f32 v[4:5], v[118:119], v[76:77]
	v_pk_mul_f32 v[76:77], v[2:3], v[178:179] op_sel_hi:[1,0]
	v_pk_mul_f32 v[2:3], v[4:5], v[178:179] op_sel_hi:[1,0]
	v_pk_mul_f32 v[4:5], v[28:29], v[78:79]
	v_cvt_pk_bf16_f32 v2, v2, v3
	v_pk_mul_f32 v[78:79], v[4:5], v[178:179] op_sel_hi:[1,0]
	v_pk_mul_f32 v[4:5], v[74:75], v[178:179] op_sel_hi:[1,0]
	v_lshlrev_b64 v[74:75], 13, v[180:181]
	v_lshl_add_u64 v[74:75], s[12:13], 0, v[74:75]
	v_lshl_add_u64 v[74:75], v[74:75], 0, s[26:27]
	v_cvt_pk_bf16_f32 v3, v76, v77
	v_cvt_pk_bf16_f32 v4, v4, v5
	v_cvt_pk_bf16_f32 v5, v78, v79
	v_lshl_add_u64 v[74:75], v[74:75], 0, v[138:139]
	global_store_dwordx4 v[74:75], v[2:5], off
	v_pk_mul_f32 v[78:79], v[42:43], v[82:83]
	s_mov_b64 s[26:27], 0x100000
	v_pk_mul_f32 v[2:3], v[124:125], v[92:93]
	v_pk_mul_f32 v[4:5], v[120:121], v[84:85]
	v_pk_mul_f32 v[76:77], v[2:3], v[178:179] op_sel_hi:[1,0]
	v_pk_mul_f32 v[2:3], v[4:5], v[178:179] op_sel_hi:[1,0]
	v_pk_mul_f32 v[4:5], v[44:45], v[90:91]
	v_cvt_pk_bf16_f32 v2, v2, v3
	v_pk_mul_f32 v[80:81], v[4:5], v[178:179] op_sel_hi:[1,0]
	v_pk_mul_f32 v[4:5], v[78:79], v[178:179] op_sel_hi:[1,0]
	v_cvt_pk_bf16_f32 v3, v76, v77
	v_cvt_pk_bf16_f32 v4, v4, v5
	v_cvt_pk_bf16_f32 v5, v80, v81
	global_store_dwordx4 v[74:75], v[2:5], off offset:256
	s_nop 1
	v_pk_mul_f32 v[2:3], v[122:123], v[68:69]
	v_pk_mul_f32 v[4:5], v[118:119], v[66:67]
	v_pk_mul_f32 v[66:67], v[2:3], v[170:171] op_sel_hi:[1,0]
	v_pk_mul_f32 v[2:3], v[4:5], v[170:171] op_sel_hi:[1,0]
	v_pk_mul_f32 v[4:5], v[28:29], v[64:65]
	v_cvt_pk_bf16_f32 v2, v2, v3
	v_pk_mul_f32 v[64:65], v[4:5], v[170:171] op_sel_hi:[1,0]
	v_pk_mul_f32 v[4:5], v[62:63], v[170:171] op_sel_hi:[1,0]
	v_lshl_add_u64 v[62:63], v[166:167], 0, s[26:27]
	s_mov_b32 s26, 0x100000
	v_cvt_pk_bf16_f32 v4, v4, v5
	v_cvt_pk_bf16_f32 v5, v64, v65
	v_add_co_u32_e32 v64, vcc, s26, v166
	v_cvt_pk_bf16_f32 v3, v66, v67
	s_nop 0
	v_addc_co_u32_e32 v65, vcc, 0, v167, vcc
	global_store_dwordx4 v[64:65], v[2:5], off
	v_pk_mul_f32 v[66:67], v[42:43], v[70:71]
	s_mov_b64 s[26:27], 0x120000
	v_pk_mul_f32 v[2:3], v[124:125], v[88:89]
	v_pk_mul_f32 v[4:5], v[120:121], v[72:73]
	v_pk_mul_f32 v[64:65], v[2:3], v[170:171] op_sel_hi:[1,0]
	v_pk_mul_f32 v[2:3], v[4:5], v[170:171] op_sel_hi:[1,0]
	v_pk_mul_f32 v[4:5], v[44:45], v[86:87]
	v_cvt_pk_bf16_f32 v2, v2, v3
	v_pk_mul_f32 v[68:69], v[4:5], v[170:171] op_sel_hi:[1,0]
	v_pk_mul_f32 v[4:5], v[66:67], v[170:171] op_sel_hi:[1,0]
	v_cvt_pk_bf16_f32 v3, v64, v65
	v_cvt_pk_bf16_f32 v4, v4, v5
	v_cvt_pk_bf16_f32 v5, v68, v69
	global_store_dwordx4 v[62:63], v[2:5], off offset:256
	s_nop 1
	v_pk_mul_f32 v[2:3], v[122:123], v[54:55]
	v_pk_mul_f32 v[4:5], v[118:119], v[48:49]
	v_pk_mul_f32 v[48:49], v[2:3], v[156:157] op_sel_hi:[1,0]
	v_pk_mul_f32 v[2:3], v[4:5], v[156:157] op_sel_hi:[1,0]
	v_pk_mul_f32 v[4:5], v[28:29], v[50:51]
	v_cvt_pk_bf16_f32 v2, v2, v3
	v_pk_mul_f32 v[50:51], v[4:5], v[156:157] op_sel_hi:[1,0]
	v_pk_mul_f32 v[4:5], v[46:47], v[156:157] op_sel_hi:[1,0]
	v_lshl_add_u64 v[46:47], v[166:167], 0, s[26:27]
	s_mov_b32 s26, 0x120000
	v_cvt_pk_bf16_f32 v3, v48, v49
	v_add_co_u32_e32 v48, vcc, s26, v166
	v_cvt_pk_bf16_f32 v4, v4, v5
	v_cvt_pk_bf16_f32 v5, v50, v51
	v_addc_co_u32_e32 v49, vcc, 0, v167, vcc
	global_store_dwordx4 v[48:49], v[2:5], off
	v_pk_mul_f32 v[50:51], v[42:43], v[52:53]
	s_mov_b64 s[26:27], 0x140000
	v_pk_mul_f32 v[2:3], v[124:125], v[60:61]
	v_pk_mul_f32 v[4:5], v[120:121], v[56:57]
	v_pk_mul_f32 v[48:49], v[2:3], v[156:157] op_sel_hi:[1,0]
	v_pk_mul_f32 v[2:3], v[4:5], v[156:157] op_sel_hi:[1,0]
	v_pk_mul_f32 v[4:5], v[44:45], v[58:59]
	v_cvt_pk_bf16_f32 v2, v2, v3
	v_pk_mul_f32 v[52:53], v[4:5], v[156:157] op_sel_hi:[1,0]
	v_pk_mul_f32 v[4:5], v[50:51], v[156:157] op_sel_hi:[1,0]
	v_cvt_pk_bf16_f32 v3, v48, v49
	v_cvt_pk_bf16_f32 v4, v4, v5
	v_cvt_pk_bf16_f32 v5, v52, v53
	global_store_dwordx4 v[46:47], v[2:5], off offset:256
	s_nop 1
	v_pk_mul_f32 v[2:3], v[122:123], v[32:33]
	v_pk_mul_f32 v[4:5], v[118:119], v[24:25]
	v_pk_mul_f32 v[24:25], v[2:3], v[128:129] op_sel_hi:[1,0]
	v_pk_mul_f32 v[2:3], v[4:5], v[128:129] op_sel_hi:[1,0]
	v_pk_mul_f32 v[4:5], v[28:29], v[30:31]
	v_cvt_pk_bf16_f32 v2, v2, v3
	v_pk_mul_f32 v[30:31], v[4:5], v[128:129] op_sel_hi:[1,0]
	v_pk_mul_f32 v[4:5], v[22:23], v[128:129] op_sel_hi:[1,0]
	v_lshl_add_u64 v[22:23], v[166:167], 0, s[26:27]
	s_mov_b32 s26, 0x140000
	v_cvt_pk_bf16_f32 v3, v24, v25
	v_add_co_u32_e32 v24, vcc, s26, v166
	v_cvt_pk_bf16_f32 v4, v4, v5
	v_cvt_pk_bf16_f32 v5, v30, v31
	v_addc_co_u32_e32 v25, vcc, 0, v167, vcc
	global_store_dwordx4 v[24:25], v[2:5], off
	v_pk_mul_f32 v[30:31], v[42:43], v[34:35]
	s_mov_b64 s[26:27], 0x160000
	v_pk_mul_f32 v[2:3], v[124:125], v[40:41]
	v_pk_mul_f32 v[4:5], v[120:121], v[36:37]
	v_pk_mul_f32 v[24:25], v[2:3], v[128:129] op_sel_hi:[1,0]
	v_pk_mul_f32 v[2:3], v[4:5], v[128:129] op_sel_hi:[1,0]
	v_pk_mul_f32 v[4:5], v[44:45], v[38:39]
	v_cvt_pk_bf16_f32 v2, v2, v3
	v_pk_mul_f32 v[32:33], v[4:5], v[128:129] op_sel_hi:[1,0]
	v_pk_mul_f32 v[4:5], v[30:31], v[128:129] op_sel_hi:[1,0]
	v_cvt_pk_bf16_f32 v3, v24, v25
	v_cvt_pk_bf16_f32 v4, v4, v5
	v_cvt_pk_bf16_f32 v5, v32, v33
	global_store_dwordx4 v[22:23], v[2:5], off offset:256
	s_nop 1
	v_pk_mul_f32 v[2:3], v[122:123], v[16:17]
	v_pk_mul_f32 v[4:5], v[118:119], v[12:13]
	v_pk_mul_f32 v[12:13], v[2:3], v[126:127] op_sel_hi:[1,0]
	v_pk_mul_f32 v[2:3], v[4:5], v[126:127] op_sel_hi:[1,0]
	v_pk_mul_f32 v[4:5], v[28:29], v[14:15]
	v_cvt_pk_bf16_f32 v2, v2, v3
	v_pk_mul_f32 v[14:15], v[4:5], v[126:127] op_sel_hi:[1,0]
	v_pk_mul_f32 v[4:5], v[10:11], v[126:127] op_sel_hi:[1,0]
	v_lshl_add_u64 v[10:11], v[166:167], 0, s[26:27]
	s_mov_b32 s26, 0x160000
	v_cvt_pk_bf16_f32 v3, v12, v13
	v_add_co_u32_e32 v12, vcc, s26, v166
	v_cvt_pk_bf16_f32 v4, v4, v5
	v_cvt_pk_bf16_f32 v5, v14, v15
	v_addc_co_u32_e32 v13, vcc, 0, v167, vcc
	global_store_dwordx4 v[12:13], v[2:5], off
	s_mov_b64 s[26:27], -1
	s_and_b64 vcc, exec, s[0:1]
	v_pk_mul_f32 v[2:3], v[124:125], v[20:21]
	v_pk_mul_f32 v[4:5], v[120:121], v[18:19]
	v_pk_mul_f32 v[12:13], v[2:3], v[126:127] op_sel_hi:[1,0]
	v_pk_mul_f32 v[2:3], v[4:5], v[126:127] op_sel_hi:[1,0]
	v_pk_mul_f32 v[4:5], v[44:45], v[8:9]
	v_cvt_pk_bf16_f32 v2, v2, v3
	v_pk_mul_f32 v[8:9], v[4:5], v[126:127] op_sel_hi:[1,0]
	v_pk_mul_f32 v[4:5], v[6:7], v[126:127] op_sel_hi:[1,0]
	v_cvt_pk_bf16_f32 v3, v12, v13
	v_cvt_pk_bf16_f32 v4, v4, v5
	v_cvt_pk_bf16_f32 v5, v8, v9
	global_store_dwordx4 v[10:11], v[2:5], off offset:256
	s_cbranch_vccnz .LBB0_791
	s_andn2_b64 vcc, exec, s[10:11]
	s_cbranch_vccnz .LBB0_790
	s_barrier
	s_branch .LBB0_790

.LBB0_1731:
	v_mov_b32_e32 v2, v0
	s_lshl_b32 s46, s73, 8
	s_add_i32 s73, s46, s70
	s_lshl_b32 s48, s74, 8
	v_lshrrev_b32_e32 v3, 1, v2
	s_ashr_i32 s49, s48, 31
	v_and_or_b32 v2, v2, 15, s73
	v_and_or_b32 v4, v3, 24, s71
	s_lshl_b64 s[46:47], s[48:49], 2
	v_ashrrev_i32_e32 v3, 31, v2
	s_add_u32 s46, s65, s46
	v_lshlrev_b32_e32 v6, 2, v4
	v_or_b32_e32 v150, s48, v4
	v_mov_b32_e32 v151, s49
	v_lshlrev_b64 v[4:5], 12, v[2:3]
	s_addc_u32 s47, s66, s47
	v_lshl_add_u64 v[44:45], v[150:151], 0, v[4:5]
	global_load_dwordx4 v[14:17], v6, s[46:47]
	global_load_dwordx4 v[10:13], v6, s[46:47] offset:16
	v_lshl_add_u64 v[42:43], v[2:3], 2, s[22:23]
	v_lshl_add_u64 v[4:5], s[12:13], 0, v[44:45]
	global_load_dword v186, v[42:43], off
	global_load_dwordx2 v[190:191], v[4:5], off
	v_or_b32_e32 v188, 16, v2
	v_or_b32_e32 v176, 32, v2
	v_or_b32_e32 v154, 48, v2
	v_ashrrev_i32_e32 v189, 31, v188
	v_ashrrev_i32_e32 v177, 31, v176
	v_ashrrev_i32_e32 v155, 31, v154
	v_lshl_add_u64 v[116:117], v[188:189], 2, s[22:23]
	v_lshl_add_u64 v[192:193], v[176:177], 2, s[22:23]
	v_lshl_add_u64 v[194:195], v[154:155], 2, s[22:23]
	global_load_dwordx4 v[2:5], v6, s[46:47] offset:528
	s_nop 0
	global_load_dwordx4 v[6:9], v6, s[46:47] offset:512
	s_nop 0
	global_load_dword v98, v[42:43], off offset:512
	global_load_dword v80, v[42:43], off offset:576
	global_load_dword v62, v[42:43], off offset:640
	global_load_dword v174, v[116:117], off
	global_load_dword v152, v[192:193], off
	s_nop 0
	global_load_dword v116, v[194:195], off
	s_nop 0
	global_load_dword v42, v[42:43], off offset:704
	v_lshl_add_u64 v[192:193], v[44:45], 1, s[6:7]
	v_or_b32_e32 v194, 0x80, v44
	v_mov_b32_e32 v195, v45
	v_lshl_add_u64 v[196:197], s[12:13], 0, v[194:195]
	s_mov_b64 s[46:47], 0x80000
	s_and_b64 vcc, exec, s[2:3]
	s_mov_b64 s[2:3], -1
	global_load_dwordx2 v[206:207], v[196:197], off
	v_lshlrev_b64 v[198:199], 12, v[188:189]
	v_lshl_add_u64 v[198:199], v[198:199], 0, v[150:151]
	v_lshl_add_u64 v[200:201], s[12:13], 0, v[198:199]
	global_load_dwordx2 v[208:209], v[200:201], off
	v_lshlrev_b64 v[200:201], 12, v[188:189]
	v_lshl_add_u64 v[200:201], v[200:201], 0, v[150:151]
	v_or_b32_e32 v200, 0x80, v200
	v_lshl_add_u64 v[198:199], s[12:13], 0, v[200:201]
	global_load_dwordx2 v[212:213], v[198:199], off
	v_lshlrev_b64 v[198:199], 12, v[176:177]
	v_lshl_add_u64 v[198:199], v[198:199], 0, v[150:151]
	v_lshl_add_u64 v[200:201], s[12:13], 0, v[198:199]
	global_load_dwordx2 v[214:215], v[200:201], off
	v_lshlrev_b64 v[200:201], 12, v[176:177]
	v_lshl_add_u64 v[200:201], v[200:201], 0, v[150:151]
	v_or_b32_e32 v200, 0x80, v200
	v_lshl_add_u64 v[198:199], s[12:13], 0, v[200:201]
	global_load_dwordx2 v[216:217], v[198:199], off
	v_lshlrev_b64 v[198:199], 12, v[154:155]
	v_lshl_add_u64 v[198:199], v[198:199], 0, v[150:151]
	v_lshl_add_u64 v[200:201], s[12:13], 0, v[198:199]
	global_load_dwordx2 v[220:221], v[200:201], off
	v_lshlrev_b64 v[200:201], 12, v[154:155]
	v_lshl_add_u64 v[200:201], v[200:201], 0, v[150:151]
	v_or_b32_e32 v200, 0x80, v200
	v_lshl_add_u64 v[198:199], s[12:13], 0, v[200:201]
	global_load_dwordx2 v[222:223], v[198:199], off
	v_lshl_add_u64 v[198:199], v[44:45], 0, s[46:47]
	v_lshl_add_u64 v[200:201], s[12:13], 0, v[198:199]
	global_load_dwordx2 v[224:225], v[200:201], off
	s_mov_b64 s[100:101], 0x80080
	v_lshl_add_u64 v[198:199], v[44:45], 0, s[100:101]
	v_lshl_add_u64 v[200:201], s[12:13], 0, v[198:199]
	global_load_dwordx2 v[226:227], v[200:201], off
	s_mov_b64 s[100:101], 0x90000
	v_lshl_add_u64 v[198:199], v[44:45], 0, s[100:101]
	v_lshl_add_u64 v[200:201], s[12:13], 0, v[198:199]
	global_load_dwordx2 v[228:229], v[200:201], off
	s_mov_b64 s[100:101], 0x90080
	v_lshl_add_u64 v[198:199], v[44:45], 0, s[100:101]
	v_lshl_add_u64 v[200:201], s[12:13], 0, v[198:199]
	global_load_dwordx2 v[230:231], v[200:201], off
	v_lshl_add_u64 v[198:199], v[44:45], 0, s[36:37]
	v_lshl_add_u64 v[200:201], s[12:13], 0, v[198:199]
	global_load_dwordx2 v[232:233], v[200:201], off
	v_lshl_add_u64 v[198:199], v[44:45], 0, s[38:39]
	v_lshl_add_u64 v[200:201], s[12:13], 0, v[198:199]
	global_load_dwordx2 v[238:239], v[200:201], off
	v_lshl_add_u64 v[198:199], v[44:45], 0, s[40:41]
	v_lshl_add_u64 v[200:201], s[12:13], 0, v[198:199]
	global_load_dwordx2 v[240:241], v[200:201], off
	v_lshl_add_u64 v[198:199], v[44:45], 0, s[42:43]
	v_lshl_add_u64 v[200:201], s[12:13], 0, v[198:199]
	global_load_dwordx2 v[242:243], v[200:201], off
	s_waitcnt vmcnt(0)
	v_pk_mul_f32 v[16:17], v[16:17], s[30:31] op_sel_hi:[1,0]
	v_pk_mul_f32 v[14:15], v[14:15], s[30:31] op_sel_hi:[1,0]
	v_pk_mul_f32 v[12:13], v[12:13], s[30:31] op_sel_hi:[1,0]
	v_pk_mul_f32 v[10:11], v[10:11], s[30:31] op_sel_hi:[1,0]
	v_pk_mul_f32 v[178:179], v[16:17], v[178:179]
	v_pk_mul_f32 v[180:181], v[14:15], v[180:181]
	v_pk_mul_f32 v[184:185], v[12:13], v[184:185]
	v_pk_mul_f32 v[182:183], v[10:11], v[182:183]
	v_cvt_f32_ubyte3_e32 v199, v190
	v_cvt_f32_ubyte2_e32 v198, v190
	v_cvt_f32_ubyte1_e32 v201, v190
	v_cvt_f32_ubyte0_e32 v200, v190
	v_cvt_f32_ubyte3_e32 v203, v191
	v_cvt_f32_ubyte2_e32 v202, v191
	v_cvt_f32_ubyte1_e32 v205, v191
	v_cvt_f32_ubyte0_e32 v204, v191
	v_pk_mul_f32 v[180:181], v[180:181], v[186:187] op_sel_hi:[1,0]
	v_pk_mul_f32 v[178:179], v[178:179], v[186:187] op_sel_hi:[1,0]
	v_pk_mul_f32 v[182:183], v[182:183], v[186:187] op_sel_hi:[1,0]
	v_pk_mul_f32 v[184:185], v[184:185], v[186:187] op_sel_hi:[1,0]
	v_pk_mul_f32 v[190:191], v[200:201], s[34:35] op_sel_hi:[1,0]
	v_pk_mul_f32 v[198:199], v[198:199], s[34:35] op_sel_hi:[1,0]
	v_pk_mul_f32 v[200:201], v[204:205], s[34:35] op_sel_hi:[1,0]
	v_pk_mul_f32 v[202:203], v[202:203], s[34:35] op_sel_hi:[1,0]
	v_pk_mul_f32 v[198:199], v[178:179], v[198:199]
	v_pk_mul_f32 v[178:179], v[180:181], v[190:191]
	v_pk_mul_f32 v[184:185], v[184:185], v[202:203]
	v_pk_mul_f32 v[180:181], v[182:183], v[200:201]
	v_cvt_pk_bf16_f32 v178, v178, v179
	v_cvt_pk_bf16_f32 v179, v198, v199
	v_cvt_pk_bf16_f32 v180, v180, v181
	v_cvt_pk_bf16_f32 v181, v184, v185
	global_store_dwordx4 v[192:193], v[178:181], off
	v_pk_mul_f32 v[8:9], v[8:9], s[30:31] op_sel_hi:[1,0]
	v_pk_mul_f32 v[6:7], v[6:7], s[30:31] op_sel_hi:[1,0]
	v_pk_mul_f32 v[4:5], v[4:5], s[30:31] op_sel_hi:[1,0]
	v_pk_mul_f32 v[2:3], v[2:3], s[30:31] op_sel_hi:[1,0]
	v_pk_mul_f32 v[166:167], v[8:9], v[166:167]
	v_pk_mul_f32 v[164:165], v[6:7], v[164:165]
	v_pk_mul_f32 v[172:173], v[4:5], v[172:173]
	v_pk_mul_f32 v[170:171], v[2:3], v[170:171]
	v_lshlrev_b64 v[178:179], 12, v[188:189]
	v_pk_mul_f32 v[164:165], v[164:165], v[186:187] op_sel_hi:[1,0]
	v_pk_mul_f32 v[166:167], v[166:167], v[186:187] op_sel_hi:[1,0]
	v_pk_mul_f32 v[170:171], v[170:171], v[186:187] op_sel_hi:[1,0]
	v_pk_mul_f32 v[172:173], v[172:173], v[186:187] op_sel_hi:[1,0]
	v_lshl_add_u64 v[178:179], v[178:179], 0, v[150:151]
	v_lshl_add_u64 v[182:183], v[194:195], 1, s[6:7]
	v_lshl_add_u64 v[184:185], s[12:13], 0, v[178:179]
	v_pk_mul_f32 v[158:159], v[16:17], v[158:159]
	v_pk_mul_f32 v[156:157], v[14:15], v[156:157]
	v_pk_mul_f32 v[162:163], v[12:13], v[162:163]
	v_pk_mul_f32 v[160:161], v[10:11], v[160:161]
	v_pk_mul_f32 v[156:157], v[156:157], v[174:175] op_sel_hi:[1,0]
	v_pk_mul_f32 v[158:159], v[158:159], v[174:175] op_sel_hi:[1,0]
	v_pk_mul_f32 v[160:161], v[160:161], v[174:175] op_sel_hi:[1,0]
	v_pk_mul_f32 v[162:163], v[162:163], v[174:175] op_sel_hi:[1,0]
	v_pk_mul_f32 v[128:129], v[8:9], v[128:129]
	v_pk_mul_f32 v[126:127], v[6:7], v[126:127]
	v_pk_mul_f32 v[148:149], v[4:5], v[148:149]
	v_pk_mul_f32 v[146:147], v[2:3], v[146:147]
	v_pk_mul_f32 v[126:127], v[126:127], v[174:175] op_sel_hi:[1,0]
	v_pk_mul_f32 v[128:129], v[128:129], v[174:175] op_sel_hi:[1,0]
	v_pk_mul_f32 v[146:147], v[146:147], v[174:175] op_sel_hi:[1,0]
	v_pk_mul_f32 v[148:149], v[148:149], v[174:175] op_sel_hi:[1,0]
	v_pk_mul_f32 v[120:121], v[16:17], v[120:121]
	v_pk_mul_f32 v[118:119], v[14:15], v[118:119]
	v_pk_mul_f32 v[124:125], v[12:13], v[124:125]
	v_pk_mul_f32 v[122:123], v[10:11], v[122:123]
	v_pk_mul_f32 v[118:119], v[118:119], v[152:153] op_sel_hi:[1,0]
	v_pk_mul_f32 v[120:121], v[120:121], v[152:153] op_sel_hi:[1,0]
	v_pk_mul_f32 v[122:123], v[122:123], v[152:153] op_sel_hi:[1,0]
	v_pk_mul_f32 v[124:125], v[124:125], v[152:153] op_sel_hi:[1,0]
	v_pk_mul_f32 v[110:111], v[8:9], v[110:111]
	v_pk_mul_f32 v[108:109], v[6:7], v[108:109]
	v_pk_mul_f32 v[114:115], v[4:5], v[114:115]
	v_pk_mul_f32 v[112:113], v[2:3], v[112:113]
	v_pk_mul_f32 v[108:109], v[108:109], v[152:153] op_sel_hi:[1,0]
	v_pk_mul_f32 v[110:111], v[110:111], v[152:153] op_sel_hi:[1,0]
	v_pk_mul_f32 v[112:113], v[112:113], v[152:153] op_sel_hi:[1,0]
	v_pk_mul_f32 v[114:115], v[114:115], v[152:153] op_sel_hi:[1,0]
	v_pk_mul_f32 v[102:103], v[16:17], v[102:103]
	v_pk_mul_f32 v[100:101], v[14:15], v[100:101]
	v_pk_mul_f32 v[106:107], v[12:13], v[106:107]
	v_pk_mul_f32 v[104:105], v[10:11], v[104:105]
	v_pk_mul_f32 v[100:101], v[100:101], v[116:117] op_sel_hi:[1,0]
	v_pk_mul_f32 v[102:103], v[102:103], v[116:117] op_sel_hi:[1,0]
	v_pk_mul_f32 v[104:105], v[104:105], v[116:117] op_sel_hi:[1,0]
	v_pk_mul_f32 v[106:107], v[106:107], v[116:117] op_sel_hi:[1,0]
	v_pk_mul_f32 v[92:93], v[8:9], v[92:93]
	v_pk_mul_f32 v[90:91], v[6:7], v[90:91]
	v_pk_mul_f32 v[96:97], v[4:5], v[96:97]
	v_pk_mul_f32 v[94:95], v[2:3], v[94:95]
	v_pk_mul_f32 v[90:91], v[90:91], v[116:117] op_sel_hi:[1,0]
	v_pk_mul_f32 v[92:93], v[92:93], v[116:117] op_sel_hi:[1,0]
	v_pk_mul_f32 v[94:95], v[94:95], v[116:117] op_sel_hi:[1,0]
	v_pk_mul_f32 v[96:97], v[96:97], v[116:117] op_sel_hi:[1,0]
	v_pk_mul_f32 v[84:85], v[16:17], v[84:85]
	v_pk_mul_f32 v[82:83], v[14:15], v[82:83]
	v_pk_mul_f32 v[88:89], v[12:13], v[88:89]
	v_pk_mul_f32 v[86:87], v[10:11], v[86:87]
	v_pk_mul_f32 v[82:83], v[82:83], v[98:99] op_sel_hi:[1,0]
	v_pk_mul_f32 v[84:85], v[84:85], v[98:99] op_sel_hi:[1,0]
	v_pk_mul_f32 v[86:87], v[86:87], v[98:99] op_sel_hi:[1,0]
	v_pk_mul_f32 v[88:89], v[88:89], v[98:99] op_sel_hi:[1,0]
	v_pk_mul_f32 v[74:75], v[8:9], v[74:75]
	v_pk_mul_f32 v[72:73], v[6:7], v[72:73]
	v_pk_mul_f32 v[78:79], v[4:5], v[78:79]
	v_pk_mul_f32 v[76:77], v[2:3], v[76:77]
	v_pk_mul_f32 v[72:73], v[72:73], v[98:99] op_sel_hi:[1,0]
	v_pk_mul_f32 v[74:75], v[74:75], v[98:99] op_sel_hi:[1,0]
	v_pk_mul_f32 v[76:77], v[76:77], v[98:99] op_sel_hi:[1,0]
	v_cvt_f32_ubyte3_e32 v187, v206
	v_cvt_f32_ubyte2_e32 v186, v206
	v_cvt_f32_ubyte1_e32 v189, v206
	v_cvt_f32_ubyte0_e32 v188, v206
	v_cvt_f32_ubyte3_e32 v191, v207
	v_cvt_f32_ubyte2_e32 v190, v207
	v_cvt_f32_ubyte1_e32 v193, v207
	v_cvt_f32_ubyte0_e32 v192, v207
	v_pk_mul_f32 v[180:181], v[188:189], s[34:35] op_sel_hi:[1,0]
	v_pk_mul_f32 v[186:187], v[186:187], s[34:35] op_sel_hi:[1,0]
	v_pk_mul_f32 v[188:189], v[192:193], s[34:35] op_sel_hi:[1,0]
	v_pk_mul_f32 v[190:191], v[190:191], s[34:35] op_sel_hi:[1,0]
	v_pk_mul_f32 v[166:167], v[166:167], v[186:187]
	v_pk_mul_f32 v[164:165], v[164:165], v[180:181]
	v_pk_mul_f32 v[172:173], v[172:173], v[190:191]
	v_pk_mul_f32 v[170:171], v[170:171], v[188:189]
	v_cvt_pk_bf16_f32 v164, v164, v165
	v_cvt_pk_bf16_f32 v165, v166, v167
	v_cvt_pk_bf16_f32 v166, v170, v171
	v_cvt_pk_bf16_f32 v167, v172, v173
	global_store_dwordx4 v[182:183], v[164:167], off
	s_nop 1
	v_pk_mul_f32 v[78:79], v[78:79], v[98:99] op_sel_hi:[1,0]
	v_lshl_add_u64 v[166:167], v[178:179], 1, s[6:7]
	v_or_b32_e32 v178, 0x80, v178
	v_lshl_add_u64 v[170:171], s[12:13], 0, v[178:179]
	v_pk_mul_f32 v[66:67], v[16:17], v[66:67]
	v_pk_mul_f32 v[64:65], v[14:15], v[64:65]
	v_pk_mul_f32 v[70:71], v[12:13], v[70:71]
	v_pk_mul_f32 v[68:69], v[10:11], v[68:69]
	v_pk_mul_f32 v[64:65], v[64:65], v[80:81] op_sel_hi:[1,0]
	v_pk_mul_f32 v[66:67], v[66:67], v[80:81] op_sel_hi:[1,0]
	v_pk_mul_f32 v[68:69], v[68:69], v[80:81] op_sel_hi:[1,0]
	v_pk_mul_f32 v[70:71], v[70:71], v[80:81] op_sel_hi:[1,0]
	v_pk_mul_f32 v[56:57], v[8:9], v[56:57]
	v_pk_mul_f32 v[54:55], v[6:7], v[54:55]
	v_pk_mul_f32 v[60:61], v[4:5], v[60:61]
	v_pk_mul_f32 v[58:59], v[2:3], v[58:59]
	v_pk_mul_f32 v[54:55], v[54:55], v[80:81] op_sel_hi:[1,0]
	v_pk_mul_f32 v[56:57], v[56:57], v[80:81] op_sel_hi:[1,0]
	v_pk_mul_f32 v[58:59], v[58:59], v[80:81] op_sel_hi:[1,0]
	v_pk_mul_f32 v[60:61], v[60:61], v[80:81] op_sel_hi:[1,0]
	v_pk_mul_f32 v[48:49], v[16:17], v[48:49]
	v_pk_mul_f32 v[46:47], v[14:15], v[46:47]
	v_pk_mul_f32 v[52:53], v[12:13], v[52:53]
	v_pk_mul_f32 v[50:51], v[10:11], v[50:51]
	v_pk_mul_f32 v[46:47], v[46:47], v[62:63] op_sel_hi:[1,0]
	v_pk_mul_f32 v[48:49], v[48:49], v[62:63] op_sel_hi:[1,0]
	v_pk_mul_f32 v[50:51], v[50:51], v[62:63] op_sel_hi:[1,0]
	v_pk_mul_f32 v[52:53], v[52:53], v[62:63] op_sel_hi:[1,0]
	v_pk_mul_f32 v[36:37], v[8:9], v[36:37]
	v_pk_mul_f32 v[34:35], v[6:7], v[34:35]
	v_pk_mul_f32 v[40:41], v[4:5], v[40:41]
	v_pk_mul_f32 v[38:39], v[2:3], v[38:39]
	v_pk_mul_f32 v[34:35], v[34:35], v[62:63] op_sel_hi:[1,0]
	v_pk_mul_f32 v[36:37], v[36:37], v[62:63] op_sel_hi:[1,0]
	v_pk_mul_f32 v[38:39], v[38:39], v[62:63] op_sel_hi:[1,0]
	v_pk_mul_f32 v[40:41], v[40:41], v[62:63] op_sel_hi:[1,0]
	v_pk_mul_f32 v[16:17], v[16:17], v[28:29]
	v_pk_mul_f32 v[14:15], v[14:15], v[26:27]
	v_pk_mul_f32 v[12:13], v[12:13], v[32:33]
	v_pk_mul_f32 v[10:11], v[10:11], v[30:31]
	v_pk_mul_f32 v[14:15], v[14:15], v[42:43] op_sel_hi:[1,0]
	v_pk_mul_f32 v[16:17], v[16:17], v[42:43] op_sel_hi:[1,0]
	v_pk_mul_f32 v[10:11], v[10:11], v[42:43] op_sel_hi:[1,0]
	v_pk_mul_f32 v[12:13], v[12:13], v[42:43] op_sel_hi:[1,0]
	v_pk_mul_f32 v[8:9], v[8:9], v[20:21]
	v_pk_mul_f32 v[6:7], v[6:7], v[18:19]
	v_pk_mul_f32 v[4:5], v[4:5], v[24:25]
	v_pk_mul_f32 v[2:3], v[2:3], v[22:23]
	v_pk_mul_f32 v[6:7], v[6:7], v[42:43] op_sel_hi:[1,0]
	v_pk_mul_f32 v[8:9], v[8:9], v[42:43] op_sel_hi:[1,0]
	v_pk_mul_f32 v[2:3], v[2:3], v[42:43] op_sel_hi:[1,0]
	v_pk_mul_f32 v[4:5], v[4:5], v[42:43] op_sel_hi:[1,0]
	v_cvt_f32_ubyte3_e32 v173, v208
	v_cvt_f32_ubyte2_e32 v172, v208
	v_cvt_f32_ubyte1_e32 v181, v208
	v_cvt_f32_ubyte0_e32 v180, v208
	v_cvt_f32_ubyte3_e32 v183, v209
	v_cvt_f32_ubyte2_e32 v182, v209
	v_cvt_f32_ubyte1_e32 v185, v209
	v_cvt_f32_ubyte0_e32 v184, v209
	v_pk_mul_f32 v[164:165], v[180:181], s[34:35] op_sel_hi:[1,0]
	v_pk_mul_f32 v[172:173], v[172:173], s[34:35] op_sel_hi:[1,0]
	v_pk_mul_f32 v[180:181], v[184:185], s[34:35] op_sel_hi:[1,0]
	v_pk_mul_f32 v[182:183], v[182:183], s[34:35] op_sel_hi:[1,0]
	v_pk_mul_f32 v[158:159], v[158:159], v[172:173]
	v_pk_mul_f32 v[156:157], v[156:157], v[164:165]
	v_pk_mul_f32 v[162:163], v[162:163], v[182:183]
	v_pk_mul_f32 v[160:161], v[160:161], v[180:181]
	v_cvt_pk_bf16_f32 v156, v156, v157
	v_cvt_pk_bf16_f32 v157, v158, v159
	v_cvt_pk_bf16_f32 v158, v160, v161
	v_cvt_pk_bf16_f32 v159, v162, v163
	global_store_dwordx4 v[166:167], v[156:159], off
	s_nop 1
	v_lshl_add_u64 v[162:163], v[178:179], 1, s[6:7]
	v_lshlrev_b64 v[156:157], 12, v[176:177]
	v_lshl_add_u64 v[156:157], v[156:157], 0, v[150:151]
	v_lshl_add_u64 v[160:161], s[12:13], 0, v[156:157]
	v_cvt_f32_ubyte3_e32 v165, v212
	v_cvt_f32_ubyte2_e32 v164, v212
	v_cvt_f32_ubyte1_e32 v167, v212
	v_cvt_f32_ubyte0_e32 v166, v212
	v_cvt_f32_ubyte3_e32 v171, v213
	v_cvt_f32_ubyte2_e32 v170, v213
	v_cvt_f32_ubyte1_e32 v173, v213
	v_cvt_f32_ubyte0_e32 v172, v213
	v_pk_mul_f32 v[158:159], v[166:167], s[34:35] op_sel_hi:[1,0]
	v_pk_mul_f32 v[164:165], v[164:165], s[34:35] op_sel_hi:[1,0]
	v_pk_mul_f32 v[166:167], v[172:173], s[34:35] op_sel_hi:[1,0]
	v_pk_mul_f32 v[170:171], v[170:171], s[34:35] op_sel_hi:[1,0]
	v_pk_mul_f32 v[128:129], v[128:129], v[164:165]
	v_pk_mul_f32 v[126:127], v[126:127], v[158:159]
	v_pk_mul_f32 v[148:149], v[148:149], v[170:171]
	v_pk_mul_f32 v[146:147], v[146:147], v[166:167]
	v_cvt_pk_bf16_f32 v126, v126, v127
	v_cvt_pk_bf16_f32 v127, v128, v129
	v_cvt_pk_bf16_f32 v128, v146, v147
	v_cvt_pk_bf16_f32 v129, v148, v149
	global_store_dwordx4 v[162:163], v[126:129], off
	v_cvt_f32_ubyte3_e32 v149, v214
	v_cvt_f32_ubyte2_e32 v148, v214
	v_cvt_f32_ubyte1_e32 v159, v214
	v_cvt_f32_ubyte0_e32 v158, v214
	v_cvt_f32_ubyte3_e32 v161, v215
	v_cvt_f32_ubyte2_e32 v160, v215
	v_cvt_f32_ubyte1_e32 v163, v215
	v_cvt_f32_ubyte0_e32 v162, v215
	v_pk_mul_f32 v[126:127], v[158:159], s[34:35] op_sel_hi:[1,0]
	v_pk_mul_f32 v[148:149], v[148:149], s[34:35] op_sel_hi:[1,0]
	v_pk_mul_f32 v[158:159], v[162:163], s[34:35] op_sel_hi:[1,0]
	v_pk_mul_f32 v[160:161], v[160:161], s[34:35] op_sel_hi:[1,0]
	v_pk_mul_f32 v[120:121], v[120:121], v[148:149]
	v_pk_mul_f32 v[118:119], v[118:119], v[126:127]
	v_pk_mul_f32 v[124:125], v[124:125], v[160:161]
	v_pk_mul_f32 v[122:123], v[122:123], v[158:159]
	v_lshl_add_u64 v[128:129], v[156:157], 1, s[6:7]
	v_or_b32_e32 v156, 0x80, v156
	v_cvt_pk_bf16_f32 v118, v118, v119
	v_cvt_pk_bf16_f32 v119, v120, v121
	v_cvt_pk_bf16_f32 v120, v122, v123
	v_cvt_pk_bf16_f32 v121, v124, v125
	v_lshl_add_u64 v[146:147], s[12:13], 0, v[156:157]
	global_store_dwordx4 v[128:129], v[118:121], off
	s_nop 1
	v_lshl_add_u64 v[124:125], v[156:157], 1, s[6:7]
	v_lshlrev_b64 v[118:119], 12, v[154:155]
	v_lshl_add_u64 v[118:119], v[118:119], 0, v[150:151]
	v_lshl_add_u64 v[122:123], s[12:13], 0, v[118:119]
	v_cvt_f32_ubyte3_e32 v127, v216
	v_cvt_f32_ubyte2_e32 v126, v216
	v_cvt_f32_ubyte1_e32 v129, v216
	v_cvt_f32_ubyte0_e32 v128, v216
	v_cvt_f32_ubyte3_e32 v147, v217
	v_cvt_f32_ubyte2_e32 v146, v217
	v_cvt_f32_ubyte1_e32 v149, v217
	v_cvt_f32_ubyte0_e32 v148, v217
	v_pk_mul_f32 v[120:121], v[128:129], s[34:35] op_sel_hi:[1,0]
	v_pk_mul_f32 v[126:127], v[126:127], s[34:35] op_sel_hi:[1,0]
	v_pk_mul_f32 v[128:129], v[148:149], s[34:35] op_sel_hi:[1,0]
	v_pk_mul_f32 v[146:147], v[146:147], s[34:35] op_sel_hi:[1,0]
	v_pk_mul_f32 v[110:111], v[110:111], v[126:127]
	v_pk_mul_f32 v[108:109], v[108:109], v[120:121]
	v_pk_mul_f32 v[114:115], v[114:115], v[146:147]
	v_pk_mul_f32 v[112:113], v[112:113], v[128:129]
	v_cvt_pk_bf16_f32 v108, v108, v109
	v_cvt_pk_bf16_f32 v109, v110, v111
	v_cvt_pk_bf16_f32 v110, v112, v113
	v_cvt_pk_bf16_f32 v111, v114, v115
	global_store_dwordx4 v[124:125], v[108:111], off
	v_cvt_f32_ubyte3_e32 v115, v220
	v_cvt_f32_ubyte2_e32 v114, v220
	v_cvt_f32_ubyte1_e32 v121, v220
	v_cvt_f32_ubyte0_e32 v120, v220
	v_cvt_f32_ubyte3_e32 v123, v221
	v_cvt_f32_ubyte2_e32 v122, v221
	v_cvt_f32_ubyte1_e32 v125, v221
	v_cvt_f32_ubyte0_e32 v124, v221
	v_pk_mul_f32 v[108:109], v[120:121], s[34:35] op_sel_hi:[1,0]
	v_pk_mul_f32 v[114:115], v[114:115], s[34:35] op_sel_hi:[1,0]
	v_pk_mul_f32 v[120:121], v[124:125], s[34:35] op_sel_hi:[1,0]
	v_pk_mul_f32 v[122:123], v[122:123], s[34:35] op_sel_hi:[1,0]
	v_pk_mul_f32 v[102:103], v[102:103], v[114:115]
	v_pk_mul_f32 v[100:101], v[100:101], v[108:109]
	v_pk_mul_f32 v[106:107], v[106:107], v[122:123]
	v_pk_mul_f32 v[104:105], v[104:105], v[120:121]
	v_lshl_add_u64 v[110:111], v[118:119], 1, s[6:7]
	v_or_b32_e32 v118, 0x80, v118
	v_cvt_pk_bf16_f32 v100, v100, v101
	v_cvt_pk_bf16_f32 v101, v102, v103
	v_cvt_pk_bf16_f32 v102, v104, v105
	v_cvt_pk_bf16_f32 v103, v106, v107
	v_lshl_add_u64 v[112:113], s[12:13], 0, v[118:119]
	global_store_dwordx4 v[110:111], v[100:103], off
	s_nop 1
	v_lshl_add_u64 v[106:107], v[118:119], 1, s[6:7]
	v_lshl_add_u64 v[100:101], v[44:45], 0, s[46:47]
	v_lshl_add_u64 v[104:105], s[12:13], 0, v[100:101]
	s_mov_b64 s[46:47], 0x80080
	v_cvt_f32_ubyte3_e32 v109, v222
	v_cvt_f32_ubyte2_e32 v108, v222
	v_cvt_f32_ubyte1_e32 v111, v222
	v_cvt_f32_ubyte0_e32 v110, v222
	v_cvt_f32_ubyte3_e32 v113, v223
	v_cvt_f32_ubyte2_e32 v112, v223
	v_cvt_f32_ubyte1_e32 v115, v223
	v_cvt_f32_ubyte0_e32 v114, v223
	v_pk_mul_f32 v[102:103], v[110:111], s[34:35] op_sel_hi:[1,0]
	v_pk_mul_f32 v[108:109], v[108:109], s[34:35] op_sel_hi:[1,0]
	v_pk_mul_f32 v[110:111], v[114:115], s[34:35] op_sel_hi:[1,0]
	v_pk_mul_f32 v[112:113], v[112:113], s[34:35] op_sel_hi:[1,0]
	v_pk_mul_f32 v[92:93], v[92:93], v[108:109]
	v_pk_mul_f32 v[90:91], v[90:91], v[102:103]
	v_pk_mul_f32 v[96:97], v[96:97], v[112:113]
	v_pk_mul_f32 v[94:95], v[94:95], v[110:111]
	v_cvt_pk_bf16_f32 v90, v90, v91
	v_cvt_pk_bf16_f32 v91, v92, v93
	v_cvt_pk_bf16_f32 v92, v94, v95
	v_cvt_pk_bf16_f32 v93, v96, v97
	global_store_dwordx4 v[106:107], v[90:93], off
	s_nop 1
	v_lshl_add_u64 v[94:95], v[100:101], 1, s[6:7]
	v_lshl_add_u64 v[92:93], v[44:45], 0, s[46:47]
	v_lshl_add_u64 v[96:97], s[12:13], 0, v[92:93]
	s_mov_b64 s[46:47], 0x90000
	v_cvt_f32_ubyte3_e32 v101, v224
	v_cvt_f32_ubyte2_e32 v100, v224
	v_cvt_f32_ubyte1_e32 v103, v224
	v_cvt_f32_ubyte0_e32 v102, v224
	v_cvt_f32_ubyte3_e32 v105, v225
	v_cvt_f32_ubyte2_e32 v104, v225
	v_cvt_f32_ubyte1_e32 v107, v225
	v_cvt_f32_ubyte0_e32 v106, v225
	v_pk_mul_f32 v[90:91], v[102:103], s[34:35] op_sel_hi:[1,0]
	v_pk_mul_f32 v[100:101], v[100:101], s[34:35] op_sel_hi:[1,0]
	v_pk_mul_f32 v[102:103], v[106:107], s[34:35] op_sel_hi:[1,0]
	v_pk_mul_f32 v[104:105], v[104:105], s[34:35] op_sel_hi:[1,0]
	v_pk_mul_f32 v[84:85], v[84:85], v[100:101]
	v_pk_mul_f32 v[82:83], v[82:83], v[90:91]
	v_pk_mul_f32 v[88:89], v[88:89], v[104:105]
	v_pk_mul_f32 v[86:87], v[86:87], v[102:103]
	v_cvt_pk_bf16_f32 v82, v82, v83
	v_cvt_pk_bf16_f32 v83, v84, v85
	v_cvt_pk_bf16_f32 v84, v86, v87
	v_cvt_pk_bf16_f32 v85, v88, v89
	global_store_dwordx4 v[94:95], v[82:85], off
	s_nop 1
	v_lshl_add_u64 v[86:87], v[92:93], 1, s[6:7]
	v_lshl_add_u64 v[82:83], v[44:45], 0, s[46:47]
	v_lshl_add_u64 v[88:89], s[12:13], 0, v[82:83]
	s_mov_b64 s[46:47], 0x90080
	v_cvt_f32_ubyte3_e32 v91, v226
	v_cvt_f32_ubyte2_e32 v90, v226
	v_cvt_f32_ubyte1_e32 v93, v226
	v_cvt_f32_ubyte0_e32 v92, v226
	v_cvt_f32_ubyte3_e32 v95, v227
	v_cvt_f32_ubyte2_e32 v94, v227
	v_cvt_f32_ubyte1_e32 v97, v227
	v_cvt_f32_ubyte0_e32 v96, v227
	v_pk_mul_f32 v[84:85], v[92:93], s[34:35] op_sel_hi:[1,0]
	v_pk_mul_f32 v[90:91], v[90:91], s[34:35] op_sel_hi:[1,0]
	v_pk_mul_f32 v[92:93], v[96:97], s[34:35] op_sel_hi:[1,0]
	v_pk_mul_f32 v[94:95], v[94:95], s[34:35] op_sel_hi:[1,0]
	v_pk_mul_f32 v[74:75], v[74:75], v[90:91]
	v_pk_mul_f32 v[72:73], v[72:73], v[84:85]
	v_pk_mul_f32 v[78:79], v[78:79], v[94:95]
	v_pk_mul_f32 v[76:77], v[76:77], v[92:93]
	v_cvt_pk_bf16_f32 v72, v72, v73
	v_cvt_pk_bf16_f32 v73, v74, v75
	v_cvt_pk_bf16_f32 v74, v76, v77
	v_cvt_pk_bf16_f32 v75, v78, v79
	global_store_dwordx4 v[86:87], v[72:75], off
	s_nop 1
	v_lshl_add_u64 v[76:77], v[82:83], 1, s[6:7]
	v_lshl_add_u64 v[74:75], v[44:45], 0, s[46:47]
	v_lshl_add_u64 v[78:79], s[12:13], 0, v[74:75]
	v_cvt_f32_ubyte3_e32 v83, v228
	v_cvt_f32_ubyte2_e32 v82, v228
	v_cvt_f32_ubyte1_e32 v85, v228
	v_cvt_f32_ubyte0_e32 v84, v228
	v_cvt_f32_ubyte3_e32 v87, v229
	v_cvt_f32_ubyte2_e32 v86, v229
	v_cvt_f32_ubyte1_e32 v89, v229
	v_cvt_f32_ubyte0_e32 v88, v229
	v_pk_mul_f32 v[72:73], v[84:85], s[34:35] op_sel_hi:[1,0]
	v_pk_mul_f32 v[82:83], v[82:83], s[34:35] op_sel_hi:[1,0]
	v_pk_mul_f32 v[84:85], v[88:89], s[34:35] op_sel_hi:[1,0]
	v_pk_mul_f32 v[86:87], v[86:87], s[34:35] op_sel_hi:[1,0]
	v_pk_mul_f32 v[66:67], v[66:67], v[82:83]
	v_pk_mul_f32 v[64:65], v[64:65], v[72:73]
	v_pk_mul_f32 v[70:71], v[70:71], v[86:87]
	v_pk_mul_f32 v[68:69], v[68:69], v[84:85]
	v_cvt_pk_bf16_f32 v64, v64, v65
	v_cvt_pk_bf16_f32 v65, v66, v67
	v_cvt_pk_bf16_f32 v66, v68, v69
	v_cvt_pk_bf16_f32 v67, v70, v71
	global_store_dwordx4 v[76:77], v[64:67], off
	s_nop 1
	v_lshl_add_u64 v[68:69], v[74:75], 1, s[6:7]
	v_lshl_add_u64 v[64:65], v[44:45], 0, s[36:37]
	v_lshl_add_u64 v[70:71], s[12:13], 0, v[64:65]
	v_cvt_f32_ubyte3_e32 v73, v230
	v_cvt_f32_ubyte2_e32 v72, v230
	v_cvt_f32_ubyte1_e32 v75, v230
	v_cvt_f32_ubyte0_e32 v74, v230
	v_cvt_f32_ubyte3_e32 v77, v231
	v_cvt_f32_ubyte2_e32 v76, v231
	v_cvt_f32_ubyte1_e32 v79, v231
	v_cvt_f32_ubyte0_e32 v78, v231
	v_pk_mul_f32 v[66:67], v[74:75], s[34:35] op_sel_hi:[1,0]
	v_pk_mul_f32 v[72:73], v[72:73], s[34:35] op_sel_hi:[1,0]
	v_pk_mul_f32 v[74:75], v[78:79], s[34:35] op_sel_hi:[1,0]
	v_pk_mul_f32 v[76:77], v[76:77], s[34:35] op_sel_hi:[1,0]
	v_pk_mul_f32 v[56:57], v[56:57], v[72:73]
	v_pk_mul_f32 v[54:55], v[54:55], v[66:67]
	v_pk_mul_f32 v[60:61], v[60:61], v[76:77]
	v_pk_mul_f32 v[58:59], v[58:59], v[74:75]
	v_cvt_pk_bf16_f32 v54, v54, v55
	v_cvt_pk_bf16_f32 v55, v56, v57
	v_cvt_pk_bf16_f32 v56, v58, v59
	v_cvt_pk_bf16_f32 v57, v60, v61
	global_store_dwordx4 v[68:69], v[54:57], off
	s_nop 1
	v_lshl_add_u64 v[58:59], v[64:65], 1, s[6:7]
	v_lshl_add_u64 v[56:57], v[44:45], 0, s[38:39]
	v_lshl_add_u64 v[60:61], s[12:13], 0, v[56:57]
	v_cvt_f32_ubyte3_e32 v65, v232
	v_cvt_f32_ubyte2_e32 v64, v232
	v_cvt_f32_ubyte1_e32 v67, v232
	v_cvt_f32_ubyte0_e32 v66, v232
	v_cvt_f32_ubyte3_e32 v69, v233
	v_cvt_f32_ubyte2_e32 v68, v233
	v_cvt_f32_ubyte1_e32 v71, v233
	v_cvt_f32_ubyte0_e32 v70, v233
	v_pk_mul_f32 v[54:55], v[66:67], s[34:35] op_sel_hi:[1,0]
	v_pk_mul_f32 v[64:65], v[64:65], s[34:35] op_sel_hi:[1,0]
	v_pk_mul_f32 v[66:67], v[70:71], s[34:35] op_sel_hi:[1,0]
	v_pk_mul_f32 v[68:69], v[68:69], s[34:35] op_sel_hi:[1,0]
	v_pk_mul_f32 v[48:49], v[48:49], v[64:65]
	v_pk_mul_f32 v[46:47], v[46:47], v[54:55]
	v_pk_mul_f32 v[52:53], v[52:53], v[68:69]
	v_pk_mul_f32 v[50:51], v[50:51], v[66:67]
	v_cvt_pk_bf16_f32 v46, v46, v47
	v_cvt_pk_bf16_f32 v47, v48, v49
	v_cvt_pk_bf16_f32 v48, v50, v51
	v_cvt_pk_bf16_f32 v49, v52, v53
	global_store_dwordx4 v[58:59], v[46:49], off
	s_nop 1
	v_lshl_add_u64 v[50:51], v[56:57], 1, s[6:7]
	v_lshl_add_u64 v[46:47], v[44:45], 0, s[40:41]
	v_lshl_add_u64 v[52:53], s[12:13], 0, v[46:47]
	v_cvt_f32_ubyte3_e32 v55, v238
	v_cvt_f32_ubyte2_e32 v54, v238
	v_cvt_f32_ubyte1_e32 v57, v238
	v_cvt_f32_ubyte0_e32 v56, v238
	v_cvt_f32_ubyte3_e32 v59, v239
	v_cvt_f32_ubyte2_e32 v58, v239
	v_cvt_f32_ubyte1_e32 v61, v239
	v_cvt_f32_ubyte0_e32 v60, v239
	v_pk_mul_f32 v[48:49], v[56:57], s[34:35] op_sel_hi:[1,0]
	v_pk_mul_f32 v[54:55], v[54:55], s[34:35] op_sel_hi:[1,0]
	v_pk_mul_f32 v[56:57], v[60:61], s[34:35] op_sel_hi:[1,0]
	v_pk_mul_f32 v[58:59], v[58:59], s[34:35] op_sel_hi:[1,0]
	v_pk_mul_f32 v[36:37], v[36:37], v[54:55]
	v_pk_mul_f32 v[34:35], v[34:35], v[48:49]
	v_pk_mul_f32 v[40:41], v[40:41], v[58:59]
	v_pk_mul_f32 v[38:39], v[38:39], v[56:57]
	v_cvt_pk_bf16_f32 v34, v34, v35
	v_cvt_pk_bf16_f32 v35, v36, v37
	v_cvt_pk_bf16_f32 v36, v38, v39
	v_cvt_pk_bf16_f32 v37, v40, v41
	global_store_dwordx4 v[50:51], v[34:37], off
	s_nop 1
	v_lshl_add_u64 v[38:39], v[46:47], 1, s[6:7]
	v_lshl_add_u64 v[36:37], v[44:45], 0, s[42:43]
	v_lshl_add_u64 v[40:41], s[12:13], 0, v[36:37]
	v_cvt_f32_ubyte3_e32 v27, v240
	v_cvt_f32_ubyte2_e32 v26, v240
	v_cvt_f32_ubyte1_e32 v29, v240
	v_cvt_f32_ubyte0_e32 v28, v240
	v_cvt_f32_ubyte3_e32 v31, v241
	v_cvt_f32_ubyte2_e32 v30, v241
	v_cvt_f32_ubyte1_e32 v33, v241
	v_cvt_f32_ubyte0_e32 v32, v241
	v_pk_mul_f32 v[28:29], v[28:29], s[34:35] op_sel_hi:[1,0]
	v_pk_mul_f32 v[26:27], v[26:27], s[34:35] op_sel_hi:[1,0]
	v_pk_mul_f32 v[32:33], v[32:33], s[34:35] op_sel_hi:[1,0]
	v_pk_mul_f32 v[30:31], v[30:31], s[34:35] op_sel_hi:[1,0]
	v_pk_mul_f32 v[16:17], v[16:17], v[26:27]
	v_pk_mul_f32 v[14:15], v[14:15], v[28:29]
	v_pk_mul_f32 v[26:27], v[12:13], v[30:31]
	v_pk_mul_f32 v[12:13], v[10:11], v[32:33]
	v_cvt_pk_bf16_f32 v10, v14, v15
	v_cvt_pk_bf16_f32 v11, v16, v17
	v_cvt_pk_bf16_f32 v12, v12, v13
	v_cvt_pk_bf16_f32 v13, v26, v27
	global_store_dwordx4 v[38:39], v[10:13], off
	v_cvt_f32_ubyte3_e32 v15, v242
	v_cvt_f32_ubyte2_e32 v14, v242
	v_cvt_f32_ubyte1_e32 v17, v242
	v_cvt_f32_ubyte0_e32 v16, v242
	v_cvt_f32_ubyte3_e32 v19, v243
	v_cvt_f32_ubyte2_e32 v18, v243
	v_cvt_f32_ubyte1_e32 v21, v243
	v_cvt_f32_ubyte0_e32 v20, v243
	v_pk_mul_f32 v[10:11], v[16:17], s[34:35] op_sel_hi:[1,0]
	v_pk_mul_f32 v[14:15], v[14:15], s[34:35] op_sel_hi:[1,0]
	v_pk_mul_f32 v[16:17], v[20:21], s[34:35] op_sel_hi:[1,0]
	v_pk_mul_f32 v[18:19], v[18:19], s[34:35] op_sel_hi:[1,0]
	v_pk_mul_f32 v[8:9], v[8:9], v[14:15]
	v_pk_mul_f32 v[6:7], v[6:7], v[10:11]
	v_pk_mul_f32 v[10:11], v[4:5], v[18:19]
	v_pk_mul_f32 v[4:5], v[2:3], v[16:17]
	v_lshl_add_u64 v[12:13], v[36:37], 1, s[6:7]
	v_cvt_pk_bf16_f32 v2, v6, v7
	v_cvt_pk_bf16_f32 v3, v8, v9
	v_cvt_pk_bf16_f32 v4, v4, v5
	v_cvt_pk_bf16_f32 v5, v10, v11
	global_store_dwordx4 v[12:13], v[2:5], off
	s_cbranch_vccnz .LBB0_1718
	s_andn2_b64 vcc, exec, s[20:21]
	s_cbranch_vccnz .LBB0_1717
	s_barrier
	s_branch .LBB0_1717

.LBB0_1755:
	s_lshl_b32 s36, s65, 8
	v_mov_b32_e32 v18, v0
	s_add_i32 s65, s36, s53
	s_lshl_b32 s38, s64, 8
	v_bfe_u32 v99, v18, 4, 2
	v_and_or_b32 v20, v18, 15, s65
	v_lshl_or_b32 v26, v99, 3, s54
	s_ashr_i32 s39, s38, 31
	v_ashrrev_i32_e32 v21, 31, v20
	s_lshl_b64 s[36:37], s[38:39], 2
	v_lshlrev_b32_e32 v70, 2, v26
	v_or_b32_e32 v26, s38, v26
	v_mov_b32_e32 v27, s39
	v_lshlrev_b64 v[28:29], 12, v[20:21]
	s_add_u32 s36, s48, s36
	v_lshl_add_u64 v[28:29], v[26:27], 0, v[28:29]
	s_addc_u32 s37, s49, s37
	v_lshl_add_u64 v[18:19], v[20:21], 2, s[22:23]
	v_lshl_add_u64 v[66:67], s[18:19], 0, v[28:29]
	global_load_dwordx4 v[42:45], v70, s[36:37]
	global_load_dwordx4 v[62:65], v70, s[36:37] offset:16
	global_load_dword v200, v[18:19], off
	global_load_dwordx2 v[202:203], v[66:67], off
	v_lshlrev_b64 v[66:67], 1, v[28:29]
	v_lshl_add_u64 v[68:69], s[6:7], 0, v[66:67]
	global_load_dwordx4 v[188:191], v[68:69], off
	v_or_b32_e32 v184, 16, v20
	v_or_b32_e32 v172, 32, v20
	v_or_b32_e32 v150, 48, v20
	v_ashrrev_i32_e32 v185, 31, v184
	v_ashrrev_i32_e32 v173, 31, v172
	v_ashrrev_i32_e32 v151, 31, v150
	global_load_dwordx4 v[192:195], v70, s[36:37] offset:528
	global_load_dwordx4 v[196:199], v70, s[36:37] offset:512
	v_lshl_add_u64 v[68:69], v[184:185], 2, s[22:23]
	v_lshl_add_u64 v[70:71], v[172:173], 2, s[22:23]
	v_lshl_add_u64 v[204:205], v[150:151], 2, s[22:23]
	global_load_dword v116, v[18:19], off offset:512
	global_load_dword v98, v[18:19], off offset:576
	global_load_dword v72, v[18:19], off offset:640
	global_load_dword v186, v[68:69], off
	global_load_dword v182, v[70:71], off
	global_load_dword v160, v[204:205], off
	s_nop 0
	global_load_dword v18, v[18:19], off offset:704
	v_lshl_add_u64 v[204:205], s[10:11], 0, v[66:67]
	v_or_b32_e32 v28, 0x80, v28
	v_lshl_add_u64 v[206:207], s[18:19], 0, v[28:29]
	v_xor_b32_e32 v19, 16, v169
	global_load_dwordx2 v[212:213], v[206:207], off
	v_lshlrev_b64 v[68:69], 1, v[28:29]
	v_lshl_add_u64 v[66:67], s[6:7], 0, v[68:69]
	global_load_dwordx4 v[214:217], v[66:67], off
	s_waitcnt vmcnt(0)
	v_pk_mul_f32 v[66:67], v[44:45], s[28:29] op_sel_hi:[1,0]
	v_pk_mul_f32 v[70:71], v[42:43], s[28:29] op_sel_hi:[1,0]
	v_pk_mul_f32 v[64:65], v[64:65], s[28:29] op_sel_hi:[1,0]
	v_pk_mul_f32 v[68:69], v[62:63], s[28:29] op_sel_hi:[1,0]
	v_pk_mul_f32 v[42:43], v[66:67], v[174:175]
	v_pk_mul_f32 v[44:45], v[70:71], v[176:177]
	v_pk_mul_f32 v[62:63], v[64:65], v[180:181]
	v_pk_mul_f32 v[174:175], v[68:69], v[178:179]
	v_cvt_f32_ubyte3_e32 v177, v202
	v_cvt_f32_ubyte2_e32 v176, v202
	v_cvt_f32_ubyte1_e32 v179, v202
	v_cvt_f32_ubyte0_e32 v178, v202
	v_cvt_f32_ubyte3_e32 v181, v203
	v_cvt_f32_ubyte2_e32 v180, v203
	v_cvt_f32_ubyte1_e32 v209, v203
	v_cvt_f32_ubyte0_e32 v208, v203
	v_pk_mul_f32 v[42:43], v[42:43], v[200:201] op_sel_hi:[1,0]
	v_pk_mul_f32 v[44:45], v[44:45], v[200:201] op_sel_hi:[1,0]
	v_pk_mul_f32 v[62:63], v[62:63], v[200:201] op_sel_hi:[1,0]
	v_pk_mul_f32 v[174:175], v[174:175], v[200:201] op_sel_hi:[1,0]
	v_pk_mul_f32 v[178:179], v[178:179], s[30:31] op_sel_hi:[1,0]
	v_pk_mul_f32 v[176:177], v[176:177], s[30:31] op_sel_hi:[1,0]
	v_pk_mul_f32 v[202:203], v[208:209], s[30:31] op_sel_hi:[1,0]
	v_pk_mul_f32 v[180:181], v[180:181], s[30:31] op_sel_hi:[1,0]
	v_lshlrev_b32_e32 v208, 16, v188
	v_and_b32_e32 v209, 0xffff0000, v188
	v_lshlrev_b32_e32 v188, 16, v189
	v_and_b32_e32 v189, 0xffff0000, v189
	v_lshlrev_b32_e32 v210, 16, v190
	v_and_b32_e32 v211, 0xffff0000, v190
	v_lshlrev_b32_e32 v190, 16, v191
	v_and_b32_e32 v191, 0xffff0000, v191
	v_pk_fma_f32 v[188:189], v[42:43], v[176:177], v[188:189]
	v_pk_fma_f32 v[178:179], v[44:45], v[178:179], v[208:209]
	v_pk_fma_f32 v[180:181], v[62:63], v[180:181], v[190:191]
	v_pk_fma_f32 v[190:191], v[174:175], v[202:203], v[210:211]
	v_cvt_pk_bf16_f32 v42, v178, v179
	v_cvt_pk_bf16_f32 v43, v188, v189
	v_cvt_pk_bf16_f32 v44, v190, v191
	v_cvt_pk_bf16_f32 v45, v180, v181
	global_store_dwordx4 v[204:205], v[42:45], off
	v_lshlrev_b64 v[204:205], 1, v[28:29]
	v_lshl_add_u64 v[28:29], s[6:7], 0, v[204:205]
	v_and_b32_e32 v28, 64, v169
	v_add_u32_e32 v28, 64, v28
	v_xor_b32_e32 v29, 32, v169
	v_cmp_lt_i32_e32 vcc, v19, v28
	v_max_f32_e64 v117, |v178|, |v179|
	v_max_f32_e64 v179, |v180|, |v181|
	v_cndmask_b32_e32 v19, v169, v19, vcc
	v_cmp_lt_i32_e32 vcc, v29, v28
	v_pk_mul_f32 v[42:43], v[198:199], s[28:29] op_sel_hi:[1,0]
	v_pk_mul_f32 v[62:63], v[196:197], s[28:29] op_sel_hi:[1,0]
	v_cndmask_b32_e32 v73, v169, v29, vcc
	v_pk_mul_f32 v[28:29], v[194:195], s[28:29] op_sel_hi:[1,0]
	v_pk_mul_f32 v[44:45], v[192:193], s[28:29] op_sel_hi:[1,0]
	v_pk_mul_f32 v[170:171], v[28:29], v[170:171]
	v_max_f32_e64 v178, |v188|, |v189|
	v_max3_f32 v179, |v190|, |v191|, v179
	v_pk_mul_f32 v[164:165], v[42:43], v[164:165]
	v_pk_mul_f32 v[162:163], v[62:63], v[162:163]
	v_pk_mul_f32 v[166:167], v[44:45], v[166:167]
	v_pk_mul_f32 v[170:171], v[170:171], v[200:201] op_sel_hi:[1,0]
	v_max3_f32 v117, v117, v178, v179
	v_pk_mul_f32 v[164:165], v[164:165], v[200:201] op_sel_hi:[1,0]
	v_pk_mul_f32 v[162:163], v[162:163], v[200:201] op_sel_hi:[1,0]
	v_pk_mul_f32 v[166:167], v[166:167], v[200:201] op_sel_hi:[1,0]
	v_lshlrev_b32_e32 v19, 2, v19
	v_cmp_eq_u32_e32 vcc, 0, v99
	v_lshlrev_b32_e32 v73, 2, v73
	v_cvt_f32_ubyte3_e32 v189, v213
	v_cvt_f32_ubyte2_e32 v188, v213
	v_cvt_f32_ubyte3_e32 v179, v212
	v_cvt_f32_ubyte2_e32 v178, v212
	v_cvt_f32_ubyte1_e32 v181, v212
	v_cvt_f32_ubyte0_e32 v180, v212
	v_cvt_f32_ubyte1_e32 v191, v213
	v_cvt_f32_ubyte0_e32 v190, v213
	v_lshlrev_b32_e32 v194, 16, v216
	v_and_b32_e32 v195, 0xffff0000, v216
	v_lshlrev_b32_e32 v216, 16, v217
	v_and_b32_e32 v217, 0xffff0000, v217
	v_pk_mul_f32 v[188:189], v[188:189], s[30:31] op_sel_hi:[1,0]
	v_lshlrev_b32_e32 v192, 16, v214
	v_and_b32_e32 v193, 0xffff0000, v214
	v_lshlrev_b32_e32 v214, 16, v215
	v_and_b32_e32 v215, 0xffff0000, v215
	v_pk_mul_f32 v[180:181], v[180:181], s[30:31] op_sel_hi:[1,0]
	v_pk_mul_f32 v[178:179], v[178:179], s[30:31] op_sel_hi:[1,0]
	v_pk_mul_f32 v[190:191], v[190:191], s[30:31] op_sel_hi:[1,0]
	v_pk_fma_f32 v[170:171], v[170:171], v[188:189], v[216:217]
	v_pk_fma_f32 v[164:165], v[164:165], v[178:179], v[214:215]
	v_pk_fma_f32 v[162:163], v[162:163], v[180:181], v[192:193]
	v_pk_fma_f32 v[166:167], v[166:167], v[190:191], v[194:195]
	v_max_f32_e64 v176, |v170|, |v171|
	v_max_f32_e64 v174, |v162|, |v163|
	v_max_f32_e64 v175, |v164|, |v165|
	v_max3_f32 v176, |v166|, |v167|, v176
	v_max3_f32 v174, v174, v175, v176
	v_max3_f32 v117, v117, 0, v174
	ds_bpermute_b32 v174, v19, v117
	v_cvt_pk_bf16_f32 v162, v162, v163
	v_cvt_pk_bf16_f32 v163, v164, v165
	v_cvt_pk_bf16_f32 v164, v166, v167
	v_cvt_pk_bf16_f32 v165, v170, v171
	s_waitcnt lgkmcnt(0)
	v_max_f32_e32 v99, v174, v174
	v_max_f32_e32 v99, v117, v99
	ds_bpermute_b32 v117, v73, v99
	v_lshl_add_u64 v[166:167], s[10:11], 0, v[204:205]
	global_store_dwordx4 v[166:167], v[162:165], off
	s_and_saveexec_b64 s[36:37], vcc
	s_cbranch_execz .LBB0_1757
	v_lshl_add_u64 v[162:163], v[20:21], 2, s[20:21]
	s_waitcnt lgkmcnt(0)
	v_max_f32_e32 v21, v117, v117
	v_max_f32_e32 v99, v99, v99
	v_max_f32_e32 v21, v99, v21
	global_atomic_umax v[162:163], v21, off

.LBB0_1900:
	s_lshl_b32 s36, s40, 8
	s_add_i32 s71, s36, s60
	s_addk_i32 s36, 0xe000
	s_ashr_i32 s36, s36, 10
	s_add_i32 s36, s36, 1
	s_cmp_lt_i32 s40, 32
	s_cselect_b32 s36, 0, s36
	s_mul_hi_i32 s73, s36, 0x18000
	s_mul_i32 s72, s36, 0x18000
	v_readlane_b32 s36, v237, 38
	v_readlane_b32 s37, v237, 39
	v_readlane_b32 s39, v237, 41
	s_cselect_b32 s37, s37, s66
	s_cselect_b32 s36, s36, s65
	s_add_u32 s39, s53, s72
	s_addc_u32 s74, s54, s73
	s_lshl_b32 s72, s84, 8
	v_mov_b32_e32 v4, v0
	v_readlane_b32 s40, v237, 42
	v_readlane_b32 s41, v237, 43
	s_ashr_i32 s73, s72, 31
	v_readlane_b32 s38, v237, 40
	s_lshl_b64 s[40:41], s[72:73], 2
	v_lshrrev_b32_e32 v5, 1, v4
	s_add_u32 s38, s39, s40
	v_and_or_b32 v4, v4, 15, s71
	v_and_or_b32 v20, v5, 24, s61
	s_addc_u32 s39, s74, s41
	v_ashrrev_i32_e32 v5, 31, v4
	s_add_u32 s40, s55, s40
	v_lshlrev_b32_e32 v161, 2, v20
	v_or_b32_e32 v166, s72, v20
	v_mov_b32_e32 v167, s73
	v_lshlrev_b64 v[20:21], 12, v[4:5]
	v_lshl_add_u64 v[36:37], v[4:5], 2, s[14:15]
	s_addc_u32 s41, s56, s41
	v_lshl_add_u64 v[20:21], v[166:167], 0, v[20:21]
	global_load_dword v210, v[36:37], off
	global_load_dwordx4 v[26:29], v161, s[40:41] offset:16
	global_load_dwordx4 v[174:177], v161, s[40:41]
	global_load_dwordx4 v[178:181], v161, s[38:39] offset:16
	global_load_dwordx4 v[182:185], v161, s[38:39]
	v_lshl_add_u64 v[212:213], v[20:21], 2, s[36:37]
	global_load_dwordx4 v[186:189], v[212:213], off
	global_load_dwordx4 v[190:193], v[212:213], off offset:16
	v_or_b32_e32 v214, 16, v4
	v_or_b32_e32 v216, 32, v4
	v_or_b32_e32 v172, 48, v4
	v_ashrrev_i32_e32 v215, 31, v214
	v_ashrrev_i32_e32 v217, 31, v216
	v_ashrrev_i32_e32 v173, 31, v172
	v_lshl_add_u64 v[4:5], v[214:215], 2, s[14:15]
	v_lshl_add_u64 v[44:45], v[216:217], 2, s[14:15]
	v_lshl_add_u64 v[164:165], v[172:173], 2, s[14:15]
	global_load_dword v162, v[36:37], off offset:512
	global_load_dword v160, v[36:37], off offset:576
	global_load_dword v150, v[36:37], off offset:640
	global_load_dword v218, v[4:5], off
	global_load_dword v170, v[44:45], off
	s_nop 0
	global_load_dword v164, v[164:165], off
	s_nop 0
	global_load_dword v4, v[36:37], off offset:704
	v_lshlrev_b64 v[220:221], 1, v[20:21]
	global_load_dwordx4 v[194:197], v161, s[38:39] offset:528
	global_load_dwordx4 v[198:201], v161, s[38:39] offset:512
	v_lshl_add_u64 v[222:223], s[12:13], 0, v[220:221]
	global_load_dwordx4 v[202:205], v161, s[40:41] offset:528
	global_load_dwordx4 v[206:209], v161, s[40:41] offset:512
	v_or_b32_e32 v220, 0x100, v220
	s_and_b64 vcc, exec, s[0:1]
	s_mov_b64 s[0:1], -1
	v_readlane_b32 s42, v237, 44
	v_readlane_b32 s43, v237, 45
	v_readlane_b32 s44, v237, 46
	v_readlane_b32 s45, v237, 47
	v_readlane_b32 s46, v237, 48
	v_readlane_b32 s47, v237, 49
	v_readlane_b32 s48, v237, 50
	v_readlane_b32 s49, v237, 51
	v_readlane_b32 s50, v237, 52
	v_readlane_b32 s51, v237, 53
	global_load_dwordx4 v[224:227], v[212:213], off offset:512
	global_load_dwordx4 v[228:231], v[212:213], off offset:528
	v_lshlrev_b64 v[36:37], 12, v[214:215]
	v_lshl_add_u64 v[36:37], v[36:37], 0, v[166:167]
	v_lshl_add_u64 v[44:45], v[36:37], 2, s[36:37]
	global_load_dwordx4 v[238:241], v[44:45], off
	v_lshlrev_b64 v[36:37], 12, v[214:215]
	v_lshl_add_u64 v[36:37], v[36:37], 0, v[166:167]
	v_lshl_add_u64 v[44:45], v[36:37], 2, s[36:37]
	global_load_dwordx4 v[242:245], v[44:45], off offset:16
	v_lshlrev_b64 v[36:37], 12, v[214:215]
	v_lshl_add_u64 v[36:37], v[36:37], 0, v[166:167]
	v_lshl_add_u64 v[44:45], v[36:37], 2, s[36:37]
	global_load_dwordx4 v[246:249], v[44:45], off offset:512
	v_lshlrev_b64 v[36:37], 12, v[214:215]
	v_lshl_add_u64 v[36:37], v[36:37], 0, v[166:167]
	v_lshl_add_u64 v[44:45], v[36:37], 2, s[36:37]
	global_load_dwordx4 v[250:253], v[44:45], off offset:528
	s_waitcnt vmcnt(0)
	v_pk_mul_f32 v[36:37], v[176:177], s[24:25] op_sel_hi:[1,0]
	v_pk_mul_f32 v[44:45], v[174:175], s[24:25] op_sel_hi:[1,0]
	v_pk_mul_f32 v[174:175], v[28:29], s[24:25] op_sel_hi:[1,0]
	v_pk_mul_f32 v[176:177], v[26:27], s[24:25] op_sel_hi:[1,0]
	v_pk_mul_f32 v[154:155], v[210:211], v[154:155] op_sel_hi:[0,1]
	v_pk_mul_f32 v[152:153], v[210:211], v[152:153] op_sel_hi:[0,1]
	v_pk_mul_f32 v[158:159], v[210:211], v[158:159] op_sel_hi:[0,1]
	v_pk_mul_f32 v[156:157], v[210:211], v[156:157] op_sel_hi:[0,1]
	v_pk_mul_f32 v[26:27], v[184:185], v[36:37]
	v_pk_mul_f32 v[28:29], v[182:183], v[44:45]
	v_pk_mul_f32 v[36:37], v[180:181], v[174:175]
	v_pk_mul_f32 v[44:45], v[178:179], v[176:177]
	v_pk_fma_f32 v[174:175], v[26:27], v[152:153], v[188:189]
	v_pk_fma_f32 v[152:153], v[28:29], v[154:155], v[186:187]
	v_pk_fma_f32 v[156:157], v[36:37], v[156:157], v[192:193]
	v_pk_fma_f32 v[154:155], v[44:45], v[158:159], v[190:191]
	v_cvt_pk_bf16_f32 v152, v152, v153
	v_cvt_pk_bf16_f32 v153, v174, v175
	v_cvt_pk_bf16_f32 v154, v154, v155
	v_cvt_pk_bf16_f32 v155, v156, v157
	global_store_dwordx4 v[222:223], v[152:155], off
	s_nop 0
	v_pk_mul_f32 v[180:181], v[210:211], v[128:129] op_sel_hi:[0,1]
	v_pk_mul_f32 v[182:183], v[210:211], v[126:127] op_sel_hi:[0,1]
	v_pk_mul_f32 v[184:185], v[210:211], v[148:149] op_sel_hi:[0,1]
	v_pk_mul_f32 v[186:187], v[210:211], v[146:147] op_sel_hi:[0,1]
	v_pk_mul_f32 v[126:127], v[208:209], s[24:25] op_sel_hi:[1,0]
	v_pk_mul_f32 v[128:129], v[206:207], s[24:25] op_sel_hi:[1,0]
	v_pk_mul_f32 v[146:147], v[204:205], s[24:25] op_sel_hi:[1,0]
	v_pk_mul_f32 v[148:149], v[202:203], s[24:25] op_sel_hi:[1,0]
	v_pk_mul_f32 v[126:127], v[200:201], v[126:127]
	v_pk_mul_f32 v[128:129], v[198:199], v[128:129]
	v_pk_mul_f32 v[146:147], v[196:197], v[146:147]
	v_pk_mul_f32 v[148:149], v[194:195], v[148:149]
	v_lshlrev_b64 v[174:175], 12, v[214:215]
	v_lshl_add_u64 v[174:175], v[174:175], 0, v[166:167]
	v_lshl_add_u64 v[178:179], s[12:13], 0, v[220:221]
	v_lshl_add_u64 v[176:177], v[174:175], 2, s[36:37]
	v_pk_mul_f32 v[122:123], v[218:219], v[122:123] op_sel_hi:[0,1]
	v_pk_mul_f32 v[118:119], v[218:219], v[118:119] op_sel_hi:[0,1]
	v_pk_mul_f32 v[124:125], v[218:219], v[124:125] op_sel_hi:[0,1]
	v_pk_mul_f32 v[120:121], v[218:219], v[120:121] op_sel_hi:[0,1]
	v_lshlrev_b64 v[174:175], 1, v[174:175]
	v_pk_mul_f32 v[112:113], v[218:219], v[112:113] op_sel_hi:[0,1]
	v_pk_mul_f32 v[110:111], v[218:219], v[110:111] op_sel_hi:[0,1]
	v_pk_mul_f32 v[116:117], v[218:219], v[116:117] op_sel_hi:[0,1]
	v_pk_mul_f32 v[114:115], v[218:219], v[114:115] op_sel_hi:[0,1]
	v_pk_mul_f32 v[104:105], v[170:171], v[104:105] op_sel_hi:[0,1]
	v_pk_mul_f32 v[102:103], v[170:171], v[102:103] op_sel_hi:[0,1]
	v_pk_mul_f32 v[108:109], v[170:171], v[108:109] op_sel_hi:[0,1]
	v_pk_mul_f32 v[106:107], v[170:171], v[106:107] op_sel_hi:[0,1]
	v_pk_mul_f32 v[96:97], v[170:171], v[96:97] op_sel_hi:[0,1]
	v_pk_mul_f32 v[94:95], v[170:171], v[94:95] op_sel_hi:[0,1]
	v_pk_mul_f32 v[100:101], v[170:171], v[100:101] op_sel_hi:[0,1]
	v_pk_mul_f32 v[98:99], v[170:171], v[98:99] op_sel_hi:[0,1]
	v_pk_mul_f32 v[88:89], v[164:165], v[88:89] op_sel_hi:[0,1]
	v_pk_mul_f32 v[86:87], v[164:165], v[86:87] op_sel_hi:[0,1]
	v_pk_mul_f32 v[92:93], v[164:165], v[92:93] op_sel_hi:[0,1]
	v_pk_mul_f32 v[90:91], v[164:165], v[90:91] op_sel_hi:[0,1]
	v_pk_mul_f32 v[80:81], v[164:165], v[80:81] op_sel_hi:[0,1]
	v_pk_mul_f32 v[78:79], v[164:165], v[78:79] op_sel_hi:[0,1]
	v_pk_mul_f32 v[84:85], v[164:165], v[84:85] op_sel_hi:[0,1]
	v_pk_mul_f32 v[82:83], v[164:165], v[82:83] op_sel_hi:[0,1]
	v_pk_mul_f32 v[72:73], v[162:163], v[72:73] op_sel_hi:[0,1]
	v_pk_mul_f32 v[70:71], v[162:163], v[70:71] op_sel_hi:[0,1]
	v_pk_mul_f32 v[76:77], v[162:163], v[76:77] op_sel_hi:[0,1]
	v_pk_mul_f32 v[74:75], v[162:163], v[74:75] op_sel_hi:[0,1]
	v_pk_mul_f32 v[64:65], v[162:163], v[64:65] op_sel_hi:[0,1]
	v_pk_mul_f32 v[62:63], v[162:163], v[62:63] op_sel_hi:[0,1]
	v_pk_mul_f32 v[68:69], v[162:163], v[68:69] op_sel_hi:[0,1]
	v_pk_mul_f32 v[66:67], v[162:163], v[66:67] op_sel_hi:[0,1]
	v_pk_mul_f32 v[58:59], v[160:161], v[58:59] op_sel_hi:[0,1]
	v_pk_mul_f32 v[54:55], v[160:161], v[54:55] op_sel_hi:[0,1]
	v_pk_mul_f32 v[60:61], v[160:161], v[60:61] op_sel_hi:[0,1]
	v_pk_mul_f32 v[56:57], v[160:161], v[56:57] op_sel_hi:[0,1]
	v_pk_mul_f32 v[48:49], v[160:161], v[48:49] op_sel_hi:[0,1]
	v_pk_mul_f32 v[46:47], v[160:161], v[46:47] op_sel_hi:[0,1]
	v_pk_mul_f32 v[52:53], v[160:161], v[52:53] op_sel_hi:[0,1]
	v_pk_mul_f32 v[50:51], v[160:161], v[50:51] op_sel_hi:[0,1]
	v_pk_mul_f32 v[40:41], v[150:151], v[40:41] op_sel_hi:[0,1]
	v_pk_mul_f32 v[38:39], v[150:151], v[38:39] op_sel_hi:[0,1]
	v_pk_mul_f32 v[42:43], v[150:151], v[42:43] op_sel_hi:[0,1]
	v_pk_mul_f32 v[34:35], v[150:151], v[34:35] op_sel_hi:[0,1]
	v_pk_mul_f32 v[22:23], v[150:151], v[22:23] op_sel_hi:[0,1]
	v_pk_mul_f32 v[30:31], v[150:151], v[30:31] op_sel_hi:[0,1]
	v_pk_mul_f32 v[14:15], v[4:5], v[14:15] op_sel_hi:[0,1]
	v_pk_mul_f32 v[12:13], v[4:5], v[12:13] op_sel_hi:[0,1]
	v_pk_mul_f32 v[18:19], v[4:5], v[18:19] op_sel_hi:[0,1]
	v_pk_mul_f32 v[16:17], v[4:5], v[16:17] op_sel_hi:[0,1]
	v_pk_mul_f32 v[10:11], v[4:5], v[10:11] op_sel_hi:[0,1]
	v_pk_mul_f32 v[6:7], v[4:5], v[6:7] op_sel_hi:[0,1]
	v_pk_mul_f32 v[8:9], v[4:5], v[8:9] op_sel_hi:[0,1]
	v_pk_mul_f32 v[2:3], v[4:5], v[2:3] op_sel_hi:[0,1]
	v_pk_fma_f32 v[226:227], v[126:127], v[182:183], v[226:227]
	v_pk_fma_f32 v[224:225], v[128:129], v[180:181], v[224:225]
	v_pk_fma_f32 v[230:231], v[146:147], v[186:187], v[230:231]
	v_pk_fma_f32 v[228:229], v[148:149], v[184:185], v[228:229]
	v_cvt_pk_bf16_f32 v224, v224, v225
	v_cvt_pk_bf16_f32 v225, v226, v227
	v_cvt_pk_bf16_f32 v226, v228, v229
	v_cvt_pk_bf16_f32 v227, v230, v231
	global_store_dwordx4 v[178:179], v[224:227], off
	s_nop 0
	v_lshl_add_u64 v[178:179], s[12:13], 0, v[174:175]
	v_or_b32_e32 v174, 0x100, v174
	v_pk_fma_f32 v[240:241], v[26:27], v[118:119], v[240:241]
	v_pk_fma_f32 v[118:119], v[28:29], v[122:123], v[238:239]
	v_pk_fma_f32 v[122:123], v[36:37], v[120:121], v[244:245]
	v_pk_fma_f32 v[120:121], v[44:45], v[124:125], v[242:243]
	v_cvt_pk_bf16_f32 v118, v118, v119
	v_cvt_pk_bf16_f32 v119, v240, v241
	v_cvt_pk_bf16_f32 v120, v120, v121
	v_cvt_pk_bf16_f32 v121, v122, v123
	global_store_dwordx4 v[178:179], v[118:121], off
	s_nop 0
	v_lshlrev_b64 v[152:153], 12, v[216:217]
	v_lshl_add_u64 v[152:153], v[152:153], 0, v[166:167]
	v_lshl_add_u64 v[156:157], s[12:13], 0, v[174:175]
	v_lshl_add_u64 v[154:155], v[152:153], 2, s[36:37]
	v_pk_fma_f32 v[248:249], v[126:127], v[110:111], v[248:249]
	v_pk_fma_f32 v[110:111], v[128:129], v[112:113], v[246:247]
	v_pk_fma_f32 v[114:115], v[146:147], v[114:115], v[252:253]
	v_pk_fma_f32 v[112:113], v[148:149], v[116:117], v[250:251]
	v_cvt_pk_bf16_f32 v110, v110, v111
	v_cvt_pk_bf16_f32 v111, v248, v249
	global_load_dwordx4 v[122:125], v[154:155], off
	v_cvt_pk_bf16_f32 v112, v112, v113
	v_cvt_pk_bf16_f32 v113, v114, v115
	global_store_dwordx4 v[156:157], v[110:113], off
	s_nop 0
	global_load_dwordx4 v[114:117], v[154:155], off offset:16
	v_lshlrev_b64 v[118:119], 1, v[152:153]
	v_lshl_add_u64 v[120:121], s[12:13], 0, v[118:119]
	v_or_b32_e32 v118, 0x100, v118
	s_waitcnt vmcnt(0)
	v_pk_fma_f32 v[124:125], v[26:27], v[102:103], v[124:125]
	v_pk_fma_f32 v[102:103], v[28:29], v[104:105], v[122:123]
	v_pk_fma_f32 v[106:107], v[36:37], v[106:107], v[116:117]
	v_pk_fma_f32 v[104:105], v[44:45], v[108:109], v[114:115]
	v_cvt_pk_bf16_f32 v102, v102, v103
	v_cvt_pk_bf16_f32 v103, v124, v125
	global_load_dwordx4 v[122:125], v[154:155], off offset:512
	global_load_dwordx4 v[156:159], v[154:155], off offset:528
	v_lshlrev_b64 v[4:5], 12, v[172:173]
	v_lshl_add_u64 v[4:5], v[4:5], 0, v[166:167]
	v_lshl_add_u64 v[108:109], v[4:5], 2, s[36:37]
	global_load_dwordx4 v[174:177], v[108:109], off
	v_lshlrev_b64 v[4:5], 12, v[172:173]
	v_lshl_add_u64 v[4:5], v[4:5], 0, v[166:167]
	v_lshl_add_u64 v[108:109], v[4:5], 2, s[36:37]
	global_load_dwordx4 v[178:181], v[108:109], off offset:16
	v_lshlrev_b64 v[4:5], 12, v[172:173]
	v_lshl_add_u64 v[4:5], v[4:5], 0, v[166:167]
	v_lshl_add_u64 v[108:109], v[4:5], 2, s[36:37]
	global_load_dwordx4 v[182:185], v[108:109], off offset:512
	v_lshlrev_b64 v[4:5], 12, v[172:173]
	v_lshl_add_u64 v[4:5], v[4:5], 0, v[166:167]
	v_lshl_add_u64 v[108:109], v[4:5], 2, s[36:37]
	global_load_dwordx4 v[186:189], v[108:109], off offset:528
	v_lshl_add_u64 v[4:5], v[20:21], 0, s[26:27]
	v_lshl_add_u64 v[108:109], v[4:5], 2, s[36:37]
	global_load_dwordx4 v[194:197], v[108:109], off
	v_lshl_add_u64 v[4:5], v[20:21], 0, s[26:27]
	v_lshl_add_u64 v[108:109], v[4:5], 2, s[36:37]
	global_load_dwordx4 v[198:201], v[108:109], off offset:16
	v_lshl_add_u64 v[4:5], v[20:21], 0, s[26:27]
	v_lshl_add_u64 v[108:109], v[4:5], 2, s[36:37]
	global_load_dwordx4 v[202:205], v[108:109], off offset:512
	v_lshl_add_u64 v[4:5], v[20:21], 0, s[26:27]
	v_lshl_add_u64 v[108:109], v[4:5], 2, s[36:37]
	global_load_dwordx4 v[206:209], v[108:109], off offset:528
	v_lshl_add_u64 v[4:5], v[20:21], 0, s[18:19]
	v_lshl_add_u64 v[108:109], v[4:5], 2, s[36:37]
	global_load_dwordx4 v[212:215], v[108:109], off
	v_lshl_add_u64 v[4:5], v[20:21], 0, s[18:19]
	v_lshl_add_u64 v[108:109], v[4:5], 2, s[36:37]
	global_load_dwordx4 v[220:223], v[108:109], off offset:16
	v_lshl_add_u64 v[4:5], v[20:21], 0, s[18:19]
	v_lshl_add_u64 v[108:109], v[4:5], 2, s[36:37]
	global_load_dwordx4 v[224:227], v[108:109], off offset:512
	v_lshl_add_u64 v[4:5], v[20:21], 0, s[18:19]
	v_lshl_add_u64 v[108:109], v[4:5], 2, s[36:37]
	global_load_dwordx4 v[228:231], v[108:109], off offset:528
	v_lshl_add_u64 v[4:5], v[20:21], 0, s[28:29]
	v_lshl_add_u64 v[108:109], v[4:5], 2, s[36:37]
	global_load_dwordx4 v[238:241], v[108:109], off
	v_lshl_add_u64 v[4:5], v[20:21], 0, s[28:29]
	v_lshl_add_u64 v[108:109], v[4:5], 2, s[36:37]
	global_load_dwordx4 v[242:245], v[108:109], off offset:16
	v_lshl_add_u64 v[4:5], v[20:21], 0, s[28:29]
	v_lshl_add_u64 v[108:109], v[4:5], 2, s[36:37]
	global_load_dwordx4 v[246:249], v[108:109], off offset:512
	v_lshl_add_u64 v[4:5], v[20:21], 0, s[28:29]
	v_lshl_add_u64 v[108:109], v[4:5], 2, s[36:37]
	global_load_dwordx4 v[250:253], v[108:109], off offset:528
	v_cvt_pk_bf16_f32 v104, v104, v105
	v_cvt_pk_bf16_f32 v105, v106, v107
	global_store_dwordx4 v[120:121], v[102:105], off
	s_nop 0
	v_lshlrev_b64 v[110:111], 12, v[172:173]
	v_lshl_add_u64 v[110:111], v[110:111], 0, v[166:167]
	v_lshl_add_u64 v[114:115], s[12:13], 0, v[118:119]
	v_lshl_add_u64 v[112:113], v[110:111], 2, s[36:37]
	s_waitcnt vmcnt(0)
	v_pk_fma_f32 v[124:125], v[126:127], v[94:95], v[124:125]
	v_pk_fma_f32 v[94:95], v[128:129], v[96:97], v[122:123]
	v_pk_fma_f32 v[98:99], v[146:147], v[98:99], v[158:159]
	v_pk_fma_f32 v[96:97], v[148:149], v[100:101], v[156:157]
	v_cvt_pk_bf16_f32 v94, v94, v95
	v_cvt_pk_bf16_f32 v95, v124, v125
	v_cvt_pk_bf16_f32 v96, v96, v97
	v_cvt_pk_bf16_f32 v97, v98, v99
	global_store_dwordx4 v[114:115], v[94:97], off
	s_nop 0
	v_lshlrev_b64 v[102:103], 1, v[110:111]
	v_lshl_add_u64 v[104:105], s[12:13], 0, v[102:103]
	v_or_b32_e32 v102, 0x100, v102
	v_pk_fma_f32 v[176:177], v[26:27], v[86:87], v[176:177]
	v_pk_fma_f32 v[86:87], v[28:29], v[88:89], v[174:175]
	v_pk_fma_f32 v[90:91], v[36:37], v[90:91], v[180:181]
	v_pk_fma_f32 v[88:89], v[44:45], v[92:93], v[178:179]
	v_cvt_pk_bf16_f32 v86, v86, v87
	v_cvt_pk_bf16_f32 v87, v176, v177
	v_cvt_pk_bf16_f32 v88, v88, v89
	v_cvt_pk_bf16_f32 v89, v90, v91
	global_store_dwordx4 v[104:105], v[86:89], off
	s_nop 0
	v_lshl_add_u64 v[94:95], v[20:21], 0, s[26:27]
	v_lshl_add_u64 v[98:99], s[12:13], 0, v[102:103]
	v_lshl_add_u64 v[96:97], v[94:95], 2, s[36:37]
	v_pk_fma_f32 v[184:185], v[126:127], v[78:79], v[184:185]
	v_pk_fma_f32 v[78:79], v[128:129], v[80:81], v[182:183]
	v_pk_fma_f32 v[82:83], v[146:147], v[82:83], v[188:189]
	v_pk_fma_f32 v[80:81], v[148:149], v[84:85], v[186:187]
	v_cvt_pk_bf16_f32 v78, v78, v79
	v_cvt_pk_bf16_f32 v79, v184, v185
	v_cvt_pk_bf16_f32 v80, v80, v81
	v_cvt_pk_bf16_f32 v81, v82, v83
	global_store_dwordx4 v[98:99], v[78:81], off
	s_nop 0
	v_lshlrev_b64 v[86:87], 1, v[94:95]
	v_lshl_add_u64 v[88:89], s[12:13], 0, v[86:87]
	v_or_b32_e32 v86, 0x100, v86
	v_pk_fma_f32 v[196:197], v[26:27], v[70:71], v[196:197]
	v_pk_fma_f32 v[70:71], v[28:29], v[72:73], v[194:195]
	v_pk_fma_f32 v[74:75], v[36:37], v[74:75], v[200:201]
	v_pk_fma_f32 v[72:73], v[44:45], v[76:77], v[198:199]
	v_cvt_pk_bf16_f32 v70, v70, v71
	v_cvt_pk_bf16_f32 v71, v196, v197
	v_cvt_pk_bf16_f32 v72, v72, v73
	v_cvt_pk_bf16_f32 v73, v74, v75
	global_store_dwordx4 v[88:89], v[70:73], off
	s_nop 0
	v_lshl_add_u64 v[78:79], v[20:21], 0, s[18:19]
	v_lshl_add_u64 v[82:83], s[12:13], 0, v[86:87]
	v_lshl_add_u64 v[80:81], v[78:79], 2, s[36:37]
	v_pk_fma_f32 v[204:205], v[126:127], v[62:63], v[204:205]
	v_pk_fma_f32 v[62:63], v[128:129], v[64:65], v[202:203]
	v_pk_fma_f32 v[66:67], v[146:147], v[66:67], v[208:209]
	v_pk_fma_f32 v[64:65], v[148:149], v[68:69], v[206:207]
	v_cvt_pk_bf16_f32 v62, v62, v63
	v_cvt_pk_bf16_f32 v63, v204, v205
	v_cvt_pk_bf16_f32 v64, v64, v65
	v_cvt_pk_bf16_f32 v65, v66, v67
	global_store_dwordx4 v[82:83], v[62:65], off
	s_nop 0
	v_lshlrev_b64 v[70:71], 1, v[78:79]
	v_lshl_add_u64 v[72:73], s[12:13], 0, v[70:71]
	v_or_b32_e32 v70, 0x100, v70
	v_pk_fma_f32 v[214:215], v[26:27], v[54:55], v[214:215]
	v_pk_fma_f32 v[54:55], v[28:29], v[58:59], v[212:213]
	v_pk_fma_f32 v[58:59], v[36:37], v[56:57], v[222:223]
	v_pk_fma_f32 v[56:57], v[44:45], v[60:61], v[220:221]
	v_cvt_pk_bf16_f32 v54, v54, v55
	v_cvt_pk_bf16_f32 v55, v214, v215
	v_cvt_pk_bf16_f32 v56, v56, v57
	v_cvt_pk_bf16_f32 v57, v58, v59
	global_store_dwordx4 v[72:73], v[54:57], off
	s_nop 0
	v_lshl_add_u64 v[62:63], v[20:21], 0, s[28:29]
	v_lshl_add_u64 v[66:67], s[12:13], 0, v[70:71]
	v_lshl_add_u64 v[64:65], v[62:63], 2, s[36:37]
	v_pk_fma_f32 v[226:227], v[126:127], v[46:47], v[226:227]
	v_pk_fma_f32 v[46:47], v[128:129], v[48:49], v[224:225]
	v_pk_fma_f32 v[50:51], v[146:147], v[50:51], v[230:231]
	v_pk_fma_f32 v[48:49], v[148:149], v[52:53], v[228:229]
	v_cvt_pk_bf16_f32 v46, v46, v47
	v_cvt_pk_bf16_f32 v47, v226, v227
	v_cvt_pk_bf16_f32 v48, v48, v49
	v_cvt_pk_bf16_f32 v49, v50, v51
	global_store_dwordx4 v[66:67], v[46:49], off
	s_nop 0
	v_lshlrev_b64 v[54:55], 1, v[62:63]
	v_lshl_add_u64 v[56:57], s[12:13], 0, v[54:55]
	v_or_b32_e32 v54, 0x100, v54
	v_pk_fma_f32 v[240:241], v[26:27], v[38:39], v[240:241]
	v_pk_fma_f32 v[38:39], v[28:29], v[40:41], v[238:239]
	v_pk_fma_f32 v[34:35], v[36:37], v[34:35], v[244:245]
	v_pk_fma_f32 v[40:41], v[44:45], v[42:43], v[242:243]
	v_cvt_pk_bf16_f32 v38, v38, v39
	v_cvt_pk_bf16_f32 v39, v240, v241
	v_cvt_pk_bf16_f32 v40, v40, v41
	v_cvt_pk_bf16_f32 v41, v34, v35
	global_store_dwordx4 v[56:57], v[38:41], off
	s_nop 0
	v_lshl_add_u64 v[34:35], v[20:21], 0, s[30:31]
	v_pk_mul_f32 v[20:21], v[150:151], v[24:25] op_sel_hi:[0,1]
	v_pk_mul_f32 v[24:25], v[150:151], v[32:33] op_sel_hi:[0,1]
	v_lshl_add_u64 v[50:51], s[12:13], 0, v[54:55]
	v_lshl_add_u64 v[42:43], v[34:35], 2, s[36:37]
	v_pk_fma_f32 v[22:23], v[126:127], v[22:23], v[248:249]
	v_pk_fma_f32 v[20:21], v[128:129], v[20:21], v[246:247]
	v_pk_fma_f32 v[30:31], v[146:147], v[30:31], v[252:253]
	v_pk_fma_f32 v[24:25], v[148:149], v[24:25], v[250:251]
	global_load_dwordx4 v[38:41], v[42:43], off
	global_load_dwordx4 v[46:49], v[42:43], off offset:16
	global_load_dwordx4 v[52:55], v[42:43], off offset:512
	global_load_dwordx4 v[56:59], v[42:43], off offset:528
	v_cvt_pk_bf16_f32 v20, v20, v21
	v_cvt_pk_bf16_f32 v21, v22, v23
	v_cvt_pk_bf16_f32 v22, v24, v25
	v_cvt_pk_bf16_f32 v23, v30, v31
	global_store_dwordx4 v[50:51], v[20:23], off
	s_nop 0
	v_lshlrev_b64 v[24:25], 1, v[34:35]
	v_lshl_add_u64 v[34:35], s[12:13], 0, v[24:25]
	v_or_b32_e32 v24, 0x100, v24
	s_waitcnt vmcnt(0)
	v_pk_fma_f32 v[40:41], v[26:27], v[12:13], v[40:41]
	v_pk_fma_f32 v[12:13], v[28:29], v[14:15], v[38:39]
	v_pk_fma_f32 v[16:17], v[36:37], v[16:17], v[48:49]
	v_pk_fma_f32 v[14:15], v[44:45], v[18:19], v[46:47]
	v_cvt_pk_bf16_f32 v12, v12, v13
	v_cvt_pk_bf16_f32 v13, v40, v41
	v_cvt_pk_bf16_f32 v14, v14, v15
	v_cvt_pk_bf16_f32 v15, v16, v17
	global_store_dwordx4 v[34:35], v[12:15], off
	s_nop 0
	v_lshl_add_u64 v[20:21], s[12:13], 0, v[24:25]
	v_pk_fma_f32 v[4:5], v[126:127], v[6:7], v[54:55]
	v_pk_fma_f32 v[6:7], v[128:129], v[10:11], v[52:53]
	v_pk_fma_f32 v[10:11], v[146:147], v[2:3], v[58:59]
	v_pk_fma_f32 v[8:9], v[148:149], v[8:9], v[56:57]
	v_cvt_pk_bf16_f32 v2, v6, v7
	v_cvt_pk_bf16_f32 v3, v4, v5
	v_cvt_pk_bf16_f32 v4, v8, v9
	v_cvt_pk_bf16_f32 v5, v10, v11
	global_store_dwordx4 v[20:21], v[2:5], off
	s_cbranch_vccnz .LBB0_1887
	s_andn2_b64 vcc, exec, s[10:11]
	s_cbranch_vccnz .LBB0_1886
	s_barrier
	s_branch .LBB0_1886

.LBB0_2101:
	s_lshl_b32 s30, s63, 8
	s_add_i32 s36, s30, s54
	s_addk_i32 s30, 0xe000
	s_ashr_i32 s30, s30, 10
	s_add_i32 s30, s30, 1
	s_cmp_gt_i32 s63, 31
	s_cselect_b32 s30, s30, 0
	v_mov_b32_e32 v2, v0
	s_mul_hi_i32 s31, s30, 0x18000
	s_mul_i32 s30, s30, 0x18000
	s_add_u32 s37, s49, s30
	v_and_or_b32 v20, v2, 15, s36
	v_lshrrev_b32_e32 v3, 1, v2
	s_addc_u32 s63, s50, s31
	s_lshl_b32 s30, s64, 8
	v_ashrrev_i32_e32 v21, 31, v20
	v_and_or_b32 v22, v3, 24, s55
	s_ashr_i32 s31, s30, 31
	v_lshlrev_b64 v[2:3], 12, v[20:21]
	s_lshl_b64 s[34:35], s[30:31], 2
	v_lshl_add_u64 v[18:19], v[2:3], 0, s[30:31]
	s_add_u32 s34, s37, s34
	v_or_b32_e32 v2, v18, v22
	v_mov_b32_e32 v3, v19
	s_addc_u32 s35, s63, s35
	v_lshlrev_b32_e32 v23, 2, v22
	v_lshl_add_u64 v[12:13], v[2:3], 1, s[10:11]
	global_load_dwordx4 v[8:11], v23, s[34:35] offset:16
	global_load_dwordx4 v[4:7], v23, s[34:35]
	v_or_b32_e32 v21, 0x80, v22
	global_load_dwordx4 v[12:15], v[12:13], off
	v_lshl_add_u64 v[32:33], v[2:3], 2, s[86:87]
	v_or_b32_e32 v16, v18, v21
	v_mov_b32_e32 v17, v19
	v_lshl_add_u64 v[178:179], v[16:17], 1, s[10:11]
	global_load_dwordx4 v[24:27], v23, s[34:35] offset:528
	global_load_dwordx4 v[28:31], v23, s[34:35] offset:512
	s_and_b64 vcc, exec, s[0:1]
	s_mov_b64 s[0:1], -1
	global_load_dwordx4 v[182:185], v[178:179], off
	v_or_b32_e32 v2, 16, v20
	v_ashrrev_i32_e32 v3, 31, v2
	v_lshlrev_b64 v[2:3], 12, v[2:3]
	v_lshl_add_u64 v[16:17], v[2:3], 0, s[30:31]
	v_or_b32_e32 v180, v16, v22
	v_mov_b32_e32 v181, v17
	v_lshl_add_u64 v[194:195], v[180:181], 1, s[10:11]
	global_load_dwordx4 v[186:189], v[194:195], off
	v_or_b32_e32 v2, 16, v20
	v_ashrrev_i32_e32 v3, 31, v2
	v_lshlrev_b64 v[2:3], 12, v[2:3]
	v_lshl_add_u64 v[180:181], v[2:3], 0, s[30:31]
	v_or_b32_e32 v180, v180, v21
	v_lshl_add_u64 v[16:17], v[180:181], 1, s[10:11]
	global_load_dwordx4 v[194:197], v[16:17], off
	v_or_b32_e32 v2, 32, v20
	v_ashrrev_i32_e32 v3, 31, v2
	v_lshlrev_b64 v[2:3], 12, v[2:3]
	v_lshl_add_u64 v[16:17], v[2:3], 0, s[30:31]
	v_or_b32_e32 v180, v16, v22
	v_mov_b32_e32 v181, v17
	v_lshl_add_u64 v[202:203], v[180:181], 1, s[10:11]
	global_load_dwordx4 v[198:201], v[202:203], off
	v_or_b32_e32 v2, 32, v20
	v_ashrrev_i32_e32 v3, 31, v2
	v_lshlrev_b64 v[2:3], 12, v[2:3]
	v_lshl_add_u64 v[180:181], v[2:3], 0, s[30:31]
	v_or_b32_e32 v180, v180, v21
	v_lshl_add_u64 v[16:17], v[180:181], 1, s[10:11]
	global_load_dwordx4 v[202:205], v[16:17], off
	v_or_b32_e32 v2, 48, v20
	v_ashrrev_i32_e32 v3, 31, v2
	v_lshlrev_b64 v[2:3], 12, v[2:3]
	v_lshl_add_u64 v[16:17], v[2:3], 0, s[30:31]
	v_or_b32_e32 v180, v16, v22
	v_mov_b32_e32 v181, v17
	v_lshl_add_u64 v[210:211], v[180:181], 1, s[10:11]
	global_load_dwordx4 v[206:209], v[210:211], off
	v_or_b32_e32 v2, 48, v20
	v_ashrrev_i32_e32 v3, 31, v2
	v_lshlrev_b64 v[2:3], 12, v[2:3]
	v_lshl_add_u64 v[180:181], v[2:3], 0, s[30:31]
	v_or_b32_e32 v180, v180, v21
	v_lshl_add_u64 v[16:17], v[180:181], 1, s[10:11]
	global_load_dwordx4 v[210:213], v[16:17], off
	v_lshl_add_u64 v[2:3], v[18:19], 0, s[20:21]
	v_or_b32_e32 v16, v2, v22
	v_mov_b32_e32 v17, v3
	v_lshl_add_u64 v[180:181], v[16:17], 1, s[10:11]
	global_load_dwordx4 v[214:217], v[180:181], off
	v_lshl_add_u64 v[16:17], v[18:19], 0, s[20:21]
	v_or_b32_e32 v16, v16, v21
	v_lshl_add_u64 v[2:3], v[16:17], 1, s[10:11]
	global_load_dwordx4 v[218:221], v[2:3], off
	v_lshl_add_u64 v[2:3], v[18:19], 0, s[22:23]
	v_or_b32_e32 v16, v2, v22
	v_mov_b32_e32 v17, v3
	v_lshl_add_u64 v[180:181], v[16:17], 1, s[10:11]
	global_load_dwordx4 v[222:225], v[180:181], off
	v_lshl_add_u64 v[16:17], v[18:19], 0, s[22:23]
	v_or_b32_e32 v16, v16, v21
	v_lshl_add_u64 v[2:3], v[16:17], 1, s[10:11]
	global_load_dwordx4 v[226:229], v[2:3], off
	v_lshl_add_u64 v[2:3], v[18:19], 0, s[24:25]
	v_or_b32_e32 v16, v2, v22
	v_mov_b32_e32 v17, v3
	v_lshl_add_u64 v[180:181], v[16:17], 1, s[10:11]
	global_load_dwordx4 v[230:233], v[180:181], off
	s_waitcnt vmcnt(0)
	v_pk_mul_f32 v[8:9], v[8:9], s[18:19] op_sel_hi:[1,0]
	v_pk_mul_f32 v[2:3], v[6:7], s[18:19] op_sel_hi:[1,0]
	v_pk_mul_f32 v[4:5], v[4:5], s[18:19] op_sel_hi:[1,0]
	v_pk_mul_f32 v[6:7], v[10:11], s[18:19] op_sel_hi:[1,0]
	v_lshlrev_b32_e32 v10, 16, v12
	v_and_b32_e32 v11, 0xffff0000, v12
	v_lshlrev_b32_e32 v12, 16, v13
	v_and_b32_e32 v13, 0xffff0000, v13
	v_lshlrev_b32_e32 v180, 16, v14
	v_and_b32_e32 v181, 0xffff0000, v14
	v_lshlrev_b32_e32 v14, 16, v15
	v_and_b32_e32 v15, 0xffff0000, v15
	v_pk_fma_f32 v[12:13], v[156:157], v[2:3], v[12:13]
	v_pk_fma_f32 v[10:11], v[154:155], v[4:5], v[10:11]
	v_pk_fma_f32 v[16:17], v[160:161], v[6:7], v[14:15]
	v_pk_fma_f32 v[14:15], v[158:159], v[8:9], v[180:181]
	global_store_dwordx4 v[32:33], v[10:13], off nt
	global_store_dwordx4 v[32:33], v[14:17], off offset:16 nt
	s_nop 1
	v_or_b32_e32 v10, 16, v20
	v_ashrrev_i32_e32 v11, 31, v10
	v_lshlrev_b64 v[10:11], 12, v[10:11]
	v_lshl_add_u64 v[158:159], v[10:11], 0, s[30:31]
	v_pk_mul_f32 v[10:11], v[30:31], s[18:19] op_sel_hi:[1,0]
	v_pk_mul_f32 v[12:13], v[28:29], s[18:19] op_sel_hi:[1,0]
	v_pk_mul_f32 v[14:15], v[26:27], s[18:19] op_sel_hi:[1,0]
	v_pk_mul_f32 v[16:17], v[24:25], s[18:19] op_sel_hi:[1,0]
	v_or_b32_e32 v160, v158, v22
	v_mov_b32_e32 v161, v159
	v_lshl_add_u64 v[178:179], v[160:161], 1, s[10:11]
	v_or_b32_e32 v158, v158, v21
	v_lshlrev_b32_e32 v24, 16, v182
	v_and_b32_e32 v25, 0xffff0000, v182
	v_lshlrev_b32_e32 v26, 16, v183
	v_and_b32_e32 v27, 0xffff0000, v183
	v_lshlrev_b32_e32 v28, 16, v184
	v_and_b32_e32 v29, 0xffff0000, v184
	v_lshlrev_b32_e32 v30, 16, v185
	v_and_b32_e32 v31, 0xffff0000, v185
	v_pk_fma_f32 v[26:27], v[152:153], v[10:11], v[26:27]
	v_pk_fma_f32 v[24:25], v[150:151], v[12:13], v[24:25]
	v_pk_fma_f32 v[30:31], v[148:149], v[14:15], v[30:31]
	v_pk_fma_f32 v[28:29], v[146:147], v[16:17], v[28:29]
	global_store_dwordx4 v[32:33], v[24:27], off offset:512 nt
	global_store_dwordx4 v[32:33], v[28:31], off offset:528 nt
	s_nop 1
	v_lshl_add_u64 v[32:33], v[160:161], 2, s[86:87]
	v_lshl_add_u64 v[146:147], v[158:159], 1, s[10:11]
	v_lshlrev_b32_e32 v28, 16, v186
	v_and_b32_e32 v29, 0xffff0000, v186
	v_lshlrev_b32_e32 v186, 16, v187
	v_and_b32_e32 v187, 0xffff0000, v187
	v_lshlrev_b32_e32 v148, 16, v188
	v_and_b32_e32 v149, 0xffff0000, v188
	v_lshlrev_b32_e32 v30, 16, v189
	v_and_b32_e32 v31, 0xffff0000, v189
	v_pk_fma_f32 v[188:189], v[144:145], v[2:3], v[186:187]
	v_pk_fma_f32 v[186:187], v[142:143], v[4:5], v[28:29]
	v_pk_fma_f32 v[30:31], v[140:141], v[6:7], v[30:31]
	v_pk_fma_f32 v[28:29], v[138:139], v[8:9], v[148:149]
	global_store_dwordx4 v[32:33], v[186:189], off nt
	global_store_dwordx4 v[32:33], v[28:31], off offset:16 nt
	v_lshlrev_b32_e32 v144, 16, v196
	s_nop 0
	v_or_b32_e32 v28, 32, v20
	v_ashrrev_i32_e32 v29, 31, v28
	v_lshlrev_b64 v[28:29], 12, v[28:29]
	v_lshl_add_u64 v[138:139], v[28:29], 0, s[30:31]
	v_lshlrev_b32_e32 v28, 16, v194
	v_and_b32_e32 v29, 0xffff0000, v194
	v_lshlrev_b32_e32 v194, 16, v195
	v_and_b32_e32 v195, 0xffff0000, v195
	v_or_b32_e32 v140, v138, v22
	v_mov_b32_e32 v141, v139
	v_and_b32_e32 v145, 0xffff0000, v196
	v_lshlrev_b32_e32 v30, 16, v197
	v_and_b32_e32 v31, 0xffff0000, v197
	v_pk_fma_f32 v[196:197], v[136:137], v[10:11], v[194:195]
	v_pk_fma_f32 v[194:195], v[134:135], v[12:13], v[28:29]
	v_lshl_add_u64 v[142:143], v[140:141], 1, s[10:11]
	v_pk_fma_f32 v[30:31], v[132:133], v[14:15], v[30:31]
	v_pk_fma_f32 v[28:29], v[130:131], v[16:17], v[144:145]
	global_store_dwordx4 v[32:33], v[194:197], off offset:512 nt
	global_store_dwordx4 v[32:33], v[28:31], off offset:528 nt
	s_nop 1
	v_or_b32_e32 v138, v138, v21
	v_lshl_add_u64 v[32:33], v[140:141], 2, s[86:87]
	v_lshl_add_u64 v[130:131], v[138:139], 1, s[10:11]
	v_lshlrev_b32_e32 v28, 16, v198
	v_and_b32_e32 v29, 0xffff0000, v198
	v_lshlrev_b32_e32 v198, 16, v199
	v_and_b32_e32 v199, 0xffff0000, v199
	v_lshlrev_b32_e32 v132, 16, v200
	v_and_b32_e32 v133, 0xffff0000, v200
	v_lshlrev_b32_e32 v30, 16, v201
	v_and_b32_e32 v31, 0xffff0000, v201
	v_pk_fma_f32 v[200:201], v[128:129], v[2:3], v[198:199]
	v_pk_fma_f32 v[198:199], v[126:127], v[4:5], v[28:29]
	v_pk_fma_f32 v[30:31], v[124:125], v[6:7], v[30:31]
	v_pk_fma_f32 v[28:29], v[122:123], v[8:9], v[132:133]
	global_store_dwordx4 v[32:33], v[198:201], off nt
	global_store_dwordx4 v[32:33], v[28:31], off offset:16 nt
	v_lshlrev_b32_e32 v128, 16, v204
	s_nop 0
	v_or_b32_e32 v28, 48, v20
	v_ashrrev_i32_e32 v29, 31, v28
	v_lshlrev_b64 v[28:29], 12, v[28:29]
	v_lshl_add_u64 v[122:123], v[28:29], 0, s[30:31]
	v_lshlrev_b32_e32 v28, 16, v202
	v_and_b32_e32 v29, 0xffff0000, v202
	v_lshlrev_b32_e32 v202, 16, v203
	v_and_b32_e32 v203, 0xffff0000, v203
	v_or_b32_e32 v124, v122, v22
	v_mov_b32_e32 v125, v123
	v_and_b32_e32 v129, 0xffff0000, v204
	v_lshlrev_b32_e32 v30, 16, v205
	v_and_b32_e32 v31, 0xffff0000, v205
	v_pk_fma_f32 v[204:205], v[120:121], v[10:11], v[202:203]
	v_pk_fma_f32 v[202:203], v[118:119], v[12:13], v[28:29]
	v_lshl_add_u64 v[126:127], v[124:125], 1, s[10:11]
	v_pk_fma_f32 v[30:31], v[116:117], v[14:15], v[30:31]
	v_pk_fma_f32 v[28:29], v[114:115], v[16:17], v[128:129]
	global_store_dwordx4 v[32:33], v[202:205], off offset:512 nt
	global_store_dwordx4 v[32:33], v[28:31], off offset:528 nt
	s_nop 1
	v_or_b32_e32 v122, v122, v21
	v_lshl_add_u64 v[32:33], v[124:125], 2, s[86:87]
	v_lshl_add_u64 v[114:115], v[122:123], 1, s[10:11]
	v_lshlrev_b32_e32 v28, 16, v206
	v_and_b32_e32 v29, 0xffff0000, v206
	v_lshlrev_b32_e32 v206, 16, v207
	v_and_b32_e32 v207, 0xffff0000, v207
	v_lshlrev_b32_e32 v116, 16, v208
	v_and_b32_e32 v117, 0xffff0000, v208
	v_lshlrev_b32_e32 v30, 16, v209
	v_and_b32_e32 v31, 0xffff0000, v209
	v_pk_fma_f32 v[208:209], v[112:113], v[2:3], v[206:207]
	v_pk_fma_f32 v[206:207], v[110:111], v[4:5], v[28:29]
	v_pk_fma_f32 v[30:31], v[108:109], v[6:7], v[30:31]
	v_pk_fma_f32 v[28:29], v[106:107], v[8:9], v[116:117]
	global_store_dwordx4 v[32:33], v[206:209], off nt
	global_store_dwordx4 v[32:33], v[28:31], off offset:16 nt
	v_lshl_add_u64 v[106:107], v[18:19], 0, s[20:21]
	v_or_b32_e32 v108, v106, v22
	v_mov_b32_e32 v109, v107
	v_lshl_add_u64 v[110:111], v[108:109], 1, s[10:11]
	v_or_b32_e32 v106, v106, v21
	v_lshlrev_b32_e32 v28, 16, v210
	v_and_b32_e32 v29, 0xffff0000, v210
	v_lshlrev_b32_e32 v210, 16, v211
	v_and_b32_e32 v211, 0xffff0000, v211
	v_lshlrev_b32_e32 v112, 16, v212
	v_and_b32_e32 v113, 0xffff0000, v212
	v_lshlrev_b32_e32 v30, 16, v213
	v_and_b32_e32 v31, 0xffff0000, v213
	v_pk_fma_f32 v[212:213], v[104:105], v[10:11], v[210:211]
	v_pk_fma_f32 v[210:211], v[102:103], v[12:13], v[28:29]
	v_pk_fma_f32 v[30:31], v[100:101], v[14:15], v[30:31]
	v_pk_fma_f32 v[28:29], v[98:99], v[16:17], v[112:113]
	global_store_dwordx4 v[32:33], v[210:213], off offset:512 nt
	global_store_dwordx4 v[32:33], v[28:31], off offset:528 nt
	s_nop 1
	v_lshl_add_u64 v[32:33], v[108:109], 2, s[86:87]
	v_lshl_add_u64 v[98:99], v[106:107], 1, s[10:11]
	v_lshlrev_b32_e32 v28, 16, v214
	v_and_b32_e32 v29, 0xffff0000, v214
	v_lshlrev_b32_e32 v214, 16, v215
	v_and_b32_e32 v215, 0xffff0000, v215
	v_lshlrev_b32_e32 v100, 16, v216
	v_and_b32_e32 v101, 0xffff0000, v216
	v_lshlrev_b32_e32 v30, 16, v217
	v_and_b32_e32 v31, 0xffff0000, v217
	v_pk_fma_f32 v[216:217], v[96:97], v[2:3], v[214:215]
	v_pk_fma_f32 v[214:215], v[94:95], v[4:5], v[28:29]
	v_pk_fma_f32 v[30:31], v[92:93], v[6:7], v[30:31]
	v_pk_fma_f32 v[28:29], v[90:91], v[8:9], v[100:101]
	global_store_dwordx4 v[32:33], v[214:217], off nt
	global_store_dwordx4 v[32:33], v[28:31], off offset:16 nt
	v_lshl_add_u64 v[90:91], v[18:19], 0, s[22:23]
	v_or_b32_e32 v92, v90, v22
	v_mov_b32_e32 v93, v91
	v_lshl_add_u64 v[94:95], v[92:93], 1, s[10:11]
	v_or_b32_e32 v90, v90, v21
	v_lshlrev_b32_e32 v28, 16, v218
	v_and_b32_e32 v29, 0xffff0000, v218
	v_lshlrev_b32_e32 v218, 16, v219
	v_and_b32_e32 v219, 0xffff0000, v219
	v_lshlrev_b32_e32 v96, 16, v220
	v_and_b32_e32 v97, 0xffff0000, v220
	v_lshlrev_b32_e32 v30, 16, v221
	v_and_b32_e32 v31, 0xffff0000, v221
	v_pk_fma_f32 v[220:221], v[88:89], v[10:11], v[218:219]
	v_pk_fma_f32 v[218:219], v[86:87], v[12:13], v[28:29]
	v_pk_fma_f32 v[30:31], v[84:85], v[14:15], v[30:31]
	v_pk_fma_f32 v[28:29], v[82:83], v[16:17], v[96:97]
	global_store_dwordx4 v[32:33], v[218:221], off offset:512 nt
	global_store_dwordx4 v[32:33], v[28:31], off offset:528 nt
	s_nop 1
	v_lshl_add_u64 v[32:33], v[92:93], 2, s[86:87]
	v_lshl_add_u64 v[82:83], v[90:91], 1, s[10:11]
	v_lshlrev_b32_e32 v28, 16, v222
	v_and_b32_e32 v29, 0xffff0000, v222
	v_lshlrev_b32_e32 v222, 16, v223
	v_and_b32_e32 v223, 0xffff0000, v223
	v_lshlrev_b32_e32 v84, 16, v224
	v_and_b32_e32 v85, 0xffff0000, v224
	v_lshlrev_b32_e32 v30, 16, v225
	v_and_b32_e32 v31, 0xffff0000, v225
	v_pk_fma_f32 v[224:225], v[80:81], v[2:3], v[222:223]
	v_pk_fma_f32 v[222:223], v[78:79], v[4:5], v[28:29]
	v_pk_fma_f32 v[30:31], v[76:77], v[6:7], v[30:31]
	v_pk_fma_f32 v[28:29], v[74:75], v[8:9], v[84:85]
	global_store_dwordx4 v[32:33], v[222:225], off nt
	global_store_dwordx4 v[32:33], v[28:31], off offset:16 nt
	v_lshl_add_u64 v[74:75], v[18:19], 0, s[24:25]
	v_or_b32_e32 v76, v74, v22
	v_mov_b32_e32 v77, v75
	v_lshl_add_u64 v[78:79], v[76:77], 1, s[10:11]
	v_or_b32_e32 v74, v74, v21
	v_lshl_add_u64 v[18:19], v[18:19], 0, s[26:27]
	v_lshlrev_b32_e32 v28, 16, v226
	v_and_b32_e32 v29, 0xffff0000, v226
	v_lshlrev_b32_e32 v226, 16, v227
	v_and_b32_e32 v227, 0xffff0000, v227
	v_lshlrev_b32_e32 v80, 16, v228
	v_and_b32_e32 v81, 0xffff0000, v228
	v_lshlrev_b32_e32 v30, 16, v229
	v_and_b32_e32 v31, 0xffff0000, v229
	v_pk_fma_f32 v[228:229], v[72:73], v[10:11], v[226:227]
	v_pk_fma_f32 v[226:227], v[70:71], v[12:13], v[28:29]
	v_pk_fma_f32 v[30:31], v[68:69], v[14:15], v[30:31]
	v_pk_fma_f32 v[28:29], v[66:67], v[16:17], v[80:81]
	global_store_dwordx4 v[32:33], v[226:229], off offset:512 nt
	global_store_dwordx4 v[32:33], v[28:31], off offset:528 nt
	s_nop 1
	v_lshl_add_u64 v[32:33], v[76:77], 2, s[86:87]
	v_lshl_add_u64 v[66:67], v[74:75], 1, s[10:11]
	v_lshlrev_b32_e32 v28, 16, v230
	v_and_b32_e32 v29, 0xffff0000, v230
	v_lshlrev_b32_e32 v230, 16, v231
	v_and_b32_e32 v231, 0xffff0000, v231
	v_lshlrev_b32_e32 v68, 16, v232
	v_and_b32_e32 v69, 0xffff0000, v232
	v_lshlrev_b32_e32 v30, 16, v233
	v_and_b32_e32 v31, 0xffff0000, v233
	v_pk_fma_f32 v[232:233], v[64:65], v[2:3], v[230:231]
	v_pk_fma_f32 v[230:231], v[62:63], v[4:5], v[28:29]
	v_pk_fma_f32 v[30:31], v[60:61], v[6:7], v[30:31]
	v_pk_fma_f32 v[28:29], v[58:59], v[8:9], v[68:69]
	global_store_dwordx4 v[32:33], v[230:233], off nt
	global_store_dwordx4 v[32:33], v[28:31], off offset:16 nt
	global_load_dwordx4 v[24:27], v[66:67], off
	s_waitcnt vmcnt(0)
	v_and_b32_e32 v23, 0xffff0000, v24
	v_or_b32_e32 v30, v18, v22
	v_lshlrev_b32_e32 v22, 16, v24
	v_lshlrev_b32_e32 v24, 16, v25
	v_and_b32_e32 v25, 0xffff0000, v25
	v_mov_b32_e32 v31, v19
	v_lshlrev_b32_e32 v60, 16, v26
	v_and_b32_e32 v61, 0xffff0000, v26
	v_lshlrev_b32_e32 v26, 16, v27
	v_and_b32_e32 v27, 0xffff0000, v27
	v_pk_fma_f32 v[24:25], v[56:57], v[10:11], v[24:25]
	v_pk_fma_f32 v[22:23], v[54:55], v[12:13], v[22:23]
	v_lshl_add_u64 v[58:59], v[30:31], 1, s[10:11]
	v_pk_fma_f32 v[28:29], v[52:53], v[14:15], v[26:27]
	v_pk_fma_f32 v[26:27], v[50:51], v[16:17], v[60:61]
	global_store_dwordx4 v[32:33], v[22:25], off offset:512 nt
	global_store_dwordx4 v[32:33], v[26:29], off offset:528 nt
	global_load_dwordx4 v[22:25], v[58:59], off
	v_or_b32_e32 v18, v18, v21
	v_lshl_add_u64 v[28:29], v[18:19], 1, s[10:11]
	v_lshl_add_u64 v[26:27], v[30:31], 2, s[86:87]
	s_waitcnt vmcnt(0)
	v_lshlrev_b32_e32 v18, 16, v22
	v_and_b32_e32 v19, 0xffff0000, v22
	v_lshlrev_b32_e32 v20, 16, v23
	v_and_b32_e32 v21, 0xffff0000, v23
	v_lshlrev_b32_e32 v22, 16, v24
	v_and_b32_e32 v23, 0xffff0000, v24
	v_lshlrev_b32_e32 v24, 16, v25
	v_and_b32_e32 v25, 0xffff0000, v25
	v_pk_fma_f32 v[20:21], v[48:49], v[2:3], v[20:21]
	v_pk_fma_f32 v[18:19], v[46:47], v[4:5], v[18:19]
	v_pk_fma_f32 v[4:5], v[44:45], v[6:7], v[24:25]
	v_pk_fma_f32 v[2:3], v[42:43], v[8:9], v[22:23]
	global_store_dwordx4 v[26:27], v[18:21], off nt
	global_store_dwordx4 v[26:27], v[2:5], off offset:16 nt
	global_load_dwordx4 v[2:5], v[28:29], off
	s_waitcnt vmcnt(0)
	v_lshlrev_b32_e32 v6, 16, v2
	v_and_b32_e32 v7, 0xffff0000, v2
	v_lshlrev_b32_e32 v2, 16, v3
	v_and_b32_e32 v3, 0xffff0000, v3
	v_lshlrev_b32_e32 v18, 16, v4
	v_and_b32_e32 v19, 0xffff0000, v4
	v_lshlrev_b32_e32 v8, 16, v5
	v_and_b32_e32 v9, 0xffff0000, v5
	v_pk_fma_f32 v[4:5], v[40:41], v[10:11], v[2:3]
	v_pk_fma_f32 v[2:3], v[38:39], v[12:13], v[6:7]
	v_pk_fma_f32 v[8:9], v[36:37], v[14:15], v[8:9]
	v_pk_fma_f32 v[6:7], v[34:35], v[16:17], v[18:19]
	global_store_dwordx4 v[26:27], v[2:5], off offset:512 nt
	global_store_dwordx4 v[26:27], v[6:9], off offset:528 nt
	s_cbranch_vccnz .LBB0_2089
	s_andn2_b64 vcc, exec, s[8:9]
	s_cbranch_vccnz .LBB0_2088
	s_barrier
	s_branch .LBB0_2088

	.amdhsa_kernel _Z10fwd_kernel4Args
		.amdhsa_group_segment_fixed_size 0
		.amdhsa_private_segment_fixed_size 0
		.amdhsa_kernarg_size 544
		.amdhsa_user_sgpr_count 2
		.amdhsa_user_sgpr_dispatch_ptr 0
		.amdhsa_user_sgpr_queue_ptr 0
		.amdhsa_user_sgpr_kernarg_segment_ptr 1
		.amdhsa_user_sgpr_dispatch_id 0
		.amdhsa_user_sgpr_kernarg_preload_length 0
		.amdhsa_user_sgpr_kernarg_preload_offset 0
		.amdhsa_user_sgpr_private_segment_size 0
		.amdhsa_uses_dynamic_stack 0
		.amdhsa_enable_private_segment 0
		.amdhsa_system_sgpr_workgroup_id_x 1
		.amdhsa_system_sgpr_workgroup_id_y 0
		.amdhsa_system_sgpr_workgroup_id_z 0
		.amdhsa_system_sgpr_workgroup_info 0
		.amdhsa_system_vgpr_workitem_id 0
		.amdhsa_next_free_vgpr 256
		.amdhsa_next_free_sgpr 102
		.amdhsa_accum_offset 256
		.amdhsa_reserve_vcc 1
		.amdhsa_float_round_mode_32 0
		.amdhsa_float_round_mode_16_64 0
		.amdhsa_float_denorm_mode_32 3
		.amdhsa_float_denorm_mode_16_64 3
		.amdhsa_dx10_clamp 1
		.amdhsa_ieee_mode 1
		.amdhsa_fp16_overflow 0
		.amdhsa_tg_split 0
		.amdhsa_exception_fp_ieee_invalid_op 0
		.amdhsa_exception_fp_denorm_src 0
		.amdhsa_exception_fp_ieee_div_zero 0
		.amdhsa_exception_fp_ieee_overflow 0
		.amdhsa_exception_fp_ieee_underflow 0
		.amdhsa_exception_fp_ieee_inexact 0
		.amdhsa_exception_int_div_zero 0
	.end_amdhsa_kernel

amdhsa.kernels:
  - .agpr_count:     0
    .args:
      - .offset:         0
        .size:           288
        .value_kind:     by_value
      - .offset:         288
        .size:           4
        .value_kind:     hidden_block_count_x
      - .offset:         292
        .size:           4
        .value_kind:     hidden_block_count_y
      - .offset:         296
        .size:           4
        .value_kind:     hidden_block_count_z
      - .offset:         300
        .size:           2
        .value_kind:     hidden_group_size_x
      - .offset:         302
        .size:           2
        .value_kind:     hidden_group_size_y
      - .offset:         304
        .size:           2
        .value_kind:     hidden_group_size_z
      - .offset:         306
        .size:           2
        .value_kind:     hidden_remainder_x
      - .offset:         308
        .size:           2
        .value_kind:     hidden_remainder_y
      - .offset:         310
        .size:           2
        .value_kind:     hidden_remainder_z
      - .offset:         328
        .size:           8
        .value_kind:     hidden_global_offset_x
      - .offset:         336
        .size:           8
        .value_kind:     hidden_global_offset_y
      - .offset:         344
        .size:           8
        .value_kind:     hidden_global_offset_z
      - .offset:         352
        .size:           2
        .value_kind:     hidden_grid_dims
      - .offset:         408
        .size:           4
        .value_kind:     hidden_dynamic_lds_size
    .group_segment_fixed_size: 0
    .kernarg_segment_align: 8
    .kernarg_segment_size: 544
    .language:       OpenCL C
    .language_version:
      - 2
      - 0
    .max_flat_workgroup_size: 512
    .name:           _Z10fwd_kernel4Args
    .private_segment_fixed_size: 0
    .sgpr_count:     108
    .sgpr_spill_count: 123
    .symbol:         _Z10fwd_kernel4Args.kd
    .uniform_work_group_size: 1
    .uses_dynamic_stack: false
    .vgpr_count:     256
    .vgpr_spill_count: 0
    .wavefront_size: 64
